# v8: DMA addressing via scalar base + constant 32-bit lane offsets (no per-iteration 64-bit VALU pointer math), loop-invariant K fragment addresses with immediate offsets
# speedup vs baseline: 1.0397x; 1.0231x over previous
; __device__ __forceinline__ int v_rd_base(int lane) { return ((lane & 3) << 3) | (((lane >> 2) & 3) << 6) | (((lane >> 4) & 1) << 5) | (((lane >> 5) & 1) << 8); }
; #define RAWBAR() do { asm volatile("s_waitcnt lgkmcnt(0)" ::: "memory"); __builtin_amdgcn_s_barrier(); asm volatile("" ::: "memory"); } while (0)
; #define RAWBAR() do { asm volatile("s_waitcnt lgkmcnt(0)" ::: "memory"); __builtin_amdgcn_s_barrier(); asm volatile("" ::: "memory"); } while (0)
; #define RAWBAR() do { asm volatile("s_waitcnt lgkmcnt(0)" ::: "memory"); __builtin_amdgcn_s_barrier(); asm volatile("" ::: "memory"); } while (0)
; #define RAWBAR() do { asm volatile("s_waitcnt lgkmcnt(0)" ::: "memory"); __builtin_amdgcn_s_barrier(); asm volatile("" ::: "memory"); } while (0)
; #define RAWBAR() do { asm volatile("s_waitcnt lgkmcnt(0)" ::: "memory"); __builtin_amdgcn_s_barrier(); asm volatile("" ::: "memory"); } while (0)
; #define RAWBAR() do { asm volatile("s_waitcnt lgkmcnt(0)" ::: "memory"); __builtin_amdgcn_s_barrier(); asm volatile("" ::: "memory"); } while (0)
; template <int MODE> ...
;     ...
;   int tid_ = threadIdx.x; asm volatile("" : "+v"(tid_));
;   const int tid = tid_, wid = tid >> 6, lane = tid & 63, r32 = lane & 31, hi = lane >> 5, g = wid >> 1, kh = wid & 1;
;   char* K_lds = lds; char* V_lds = lds + 32768; float* L_lds = (float*)(lds + 131072);
;   constexpr float C = SCALE * 1.4426950408889634f;
;   f32x16 o[8] = {}; bf16x8 qr[8]; float lsum = 0.f;
;   const bf16* Qw = Qb + (long)(g * 32 + r32) * 128 + hi * 8;
; #pragma unroll
;   for (int d0 = 0; d0 < 8; ++d0) qr[d0] = St::ld8(Qw + d0 * 16);
;   const int vb0 = (int)(uintptr_t)V_lds + v_rd_base(lane) + 2 * kh * 4096;
;   const int krow = 32 * kh + r32;
;   typedef __attribute__((address_space(3))) unsigned lds_u32;
;   const int wu = __builtin_amdgcn_readfirstlane(wid);
;   long gk[2], gv[2];
; #pragma unroll
;   for (int c = 0; c < 2; ++c) { const int q = wu + 8 * c;
;     const int r = 4 * q + (lane >> 4), pch = lane & 15; gk[c] = (long)r * 128 + ((pch ^ (r & 7)) * 8);
;     const int st = 2 * q + (lane >> 5), kk = (st >> 2) * 8 + ((lane >> 2) & 7), k = (kk & ~0xC) | ((kk & 4) << 1) | ((kk & 8) >> 1), cc = (st & 3) * 32 + (lane & 3) * 8;
;     gv[c] = (long)k * 256 + cc; }
;     ...
;   const int NT = seq / KVBLK;
;   STAGE(0, 0); asm volatile("s_waitcnt vmcnt(0)" ::: "memory"); RAWBAR();
.LBB0_1017:
	s_mov_b64 s[24:25], -1
	s_and_b64 vcc, exec, s[22:23]
	s_cbranch_vccz .LBB0_1010
	s_ashr_i32 s29, s28, 31
	s_mul_i32 s2, s40, 0x8200
	s_lshl_b64 s[22:23], s[28:29], 7
	v_mov_b32_e32 v197, v224
	s_mul_hi_i32 s3, s40, 0x8200
	s_add_u32 s2, s2, s22
	s_addc_u32 s3, s3, s23
	v_ashrrev_i32_e32 v213, 7, v197
	v_and_b32_e32 v206, 31, v197
	v_lshlrev_b32_e32 v196, 5, v213
	s_lshl_b64 s[2:3], s[2:3], 8
	v_or_b32_e32 v0, v196, v206
	s_add_u32 s34, s52, s2
	v_ashrrev_i32_e32 v1, 31, v0
	s_addc_u32 s35, s53, s3
	s_mul_i32 s26, s40, 0x820000
	v_bfe_u32 v207, v197, 5, 1
	v_lshlrev_b64 v[0:1], 8, v[0:1]
	s_mul_hi_i32 s27, s40, 0x820000
	s_add_u32 s36, s47, s26
	v_lshl_add_u64 v[0:1], s[34:35], 0, v[0:1]
	v_lshlrev_b32_e32 v194, 4, v207
	s_addc_u32 s37, s48, s27
	v_lshl_add_u64 v[0:1], v[0:1], 0, v[194:195]
	v_ashrrev_i32_e32 v8, 6, v197
	s_add_u32 s30, s49, s26
	global_load_dwordx4 v[188:191], v[0:1], off
	global_load_dwordx4 v[184:187], v[0:1], off offset:32
	global_load_dwordx4 v[180:183], v[0:1], off offset:64
	global_load_dwordx4 v[176:179], v[0:1], off offset:96
	global_load_dwordx4 v[172:175], v[0:1], off offset:128
	global_load_dwordx4 v[168:171], v[0:1], off offset:160
	global_load_dwordx4 v[164:167], v[0:1], off offset:192
	global_load_dwordx4 v[160:163], v[0:1], off offset:224
	v_readfirstlane_b32 s2, v8
	v_bfe_u32 v0, v197, 2, 2
	v_lshrrev_b32_e32 v1, 1, v197
	s_addc_u32 s31, s50, s27
	v_bfe_u32 v4, v197, 4, 2
	v_and_or_b32 v7, v1, 8, v0
	v_lshlrev_b32_e32 v0, 3, v197
	s_lshl_b32 s3, s2, 2
	s_lshl_b32 s24, s2, 1
	v_and_b32_e32 v13, 24, v0
	v_or_b32_e32 v0, s3, v4
	s_and_b32 s3, s3, -16
	s_and_b32 s25, s24, 4
	v_and_b32_e32 v2, 63, v197
	s_or_b32 s3, s3, s25
	v_lshlrev_b32_e32 v9, 3, v2
	v_lshlrev_b32_e32 v212, 4, v2
	v_or_b32_e32 v2, s3, v7
	s_add_i32 s3, s2, 8
	v_and_or_b32 v14, s24, 2, v207
	s_lshl_b32 s24, s3, 2
	s_lshl_b32 s25, s3, 1
	v_or_b32_e32 v4, s24, v4
	s_and_b32 s24, s24, -16
	s_and_b32 s33, s25, 4
	v_and_b32_e32 v6, 15, v197
	v_ashrrev_i32_e32 v1, 31, v0
	s_or_b32 s24, s24, s33
	v_and_b32_e32 v12, 0x100, v9
	v_bitop3_b32 v11, v0, v6, 7 bitop3:0x6c
	v_ashrrev_i32_e32 v5, 31, v4
	v_bitop3_b32 v15, v4, v6, 7 bitop3:0x6c
	v_or_b32_e32 v6, s24, v7
	v_and_b32_e32 v211, 1, v8
	v_and_b32_e32 v17, 24, v9
	v_lshlrev_b64 v[8:9], 8, v[0:1]
	s_lshl_b32 s24, s2, 10
	v_lshlrev_b32_e32 v10, 1, v197
	v_and_or_b32 v16, s25, 2, v207
	v_lshl_or_b32 v8, v11, 4, v8
	s_add_i32 s25, s24, 0
	v_lshlrev_b64 v[4:5], 8, v[4:5]
	v_lshlrev_b32_e32 v15, 4, v15
	v_ashrrev_i32_e32 v3, 31, v2
	v_and_b32_e32 v19, 32, v10
	v_lshl_add_u64 v[10:11], s[36:37], 0, v[8:9]
	s_mov_b32 m0, s25
	v_or_b32_e32 v4, v4, v15
	v_ashrrev_i32_e32 v7, 31, v6
	global_load_lds_dwordx4 v[10:11], off
	v_lshl_add_u64 v[128:129], v[10:11], 0, s[18:19]
	v_lshl_add_u64 v[4:5], s[36:37], 0, v[4:5]
	v_lshl_add_u64 v[130:131], v[4:5], 0, s[18:19]
	s_add_i32 m0, s25, 0x2000
	v_lshlrev_b32_e32 v1, 6, v14
	v_lshlrev_b32_e32 v10, 1, v13
	v_lshlrev_b64 v[2:3], 9, v[2:3]
	global_load_lds_dwordx4 v[4:5], off
	s_add_i32 m0, s25, 0x4000
	s_nop 0
	global_load_lds_dwordx4 v[128:129], off
	s_add_i32 m0, s25, 0x6000
	s_nop 0
	global_load_lds_dwordx4 v[130:131], off
	v_or3_b32 v4, v1, v10, v2
	v_mov_b32_e32 v5, v3
	v_lshlrev_b32_e32 v1, 6, v16
	v_lshlrev_b64 v[6:7], 9, v[6:7]
	v_lshl_add_u64 v[4:5], s[30:31], 0, v[4:5]
	s_add_i32 m0, s25, 0x8000
	v_or3_b32 v10, v1, v10, v6
	v_mov_b32_e32 v11, v7
	global_load_lds_dwordx4 v[4:5], off
	v_lshl_add_u64 v[10:11], s[30:31], 0, v[10:11]
	s_add_i32 m0, s25, 0xa000
	v_lshl_add_u64 v[4:5], v[4:5], 0, s[10:11]
	global_load_lds_dwordx4 v[10:11], off
	s_add_i32 m0, s25, 0xc000
	s_add_i32 s33, 0, 0x8000
	global_load_lds_dwordx4 v[4:5], off
	v_lshl_add_u64 v[4:5], v[10:11], 0, s[10:11]
	s_add_i32 m0, s25, 0xe000
	v_lshlrev_b32_e32 v20, 13, v211
	global_load_lds_dwordx4 v[4:5], off
	s_cmp_lg_u32 s33, -1
	v_lshl_or_b32 v1, v206, 8, v20
	s_cselect_b32 s41, s33, 0
	s_and_b32 s2, s2, 1
	v_lshlrev_b32_e32 v4, 4, v197
	v_add_u32_e32 v216, 0, v1
	s_lshl_b32 s2, s2, 6
	v_and_b32_e32 v1, 32, v197
	v_and_b32_e32 v5, 0x70, v4
	v_bitop3_b32 v225, v194, v4, s58 bitop3:0x78
	v_or3_b32 v4, s2, v1, v13
	s_and_b32 s2, s3, 1
	s_lshl_b32 s2, s2, 6
	v_or3_b32 v1, s2, v1, v13
	v_add_u32_e32 v0, 32, v0
	v_and_b32_e32 v18, 0xc0, v212
	s_waitcnt vmcnt(0)
	v_lshl_or_b32 v6, v1, 1, v6
	v_ashrrev_i32_e32 v1, 31, v0
	s_waitcnt lgkmcnt(0)
	s_barrier
; __device__ __forceinline__ int v_rd_base(int lane) { return ((lane & 3) << 3) | (((lane >> 2) & 3) << 6) | (((lane >> 4) & 1) << 5) | (((lane >> 5) & 1) << 8); }
; #define RAWBAR() do { asm volatile("s_waitcnt lgkmcnt(0)" ::: "memory"); __builtin_amdgcn_s_barrier(); asm volatile("" ::: "memory"); } while (0)
; #define RAWBAR() do { asm volatile("s_waitcnt lgkmcnt(0)" ::: "memory"); __builtin_amdgcn_s_barrier(); asm volatile("" ::: "memory"); } while (0)
; #define RAWBAR() do { asm volatile("s_waitcnt lgkmcnt(0)" ::: "memory"); __builtin_amdgcn_s_barrier(); asm volatile("" ::: "memory"); } while (0)
; template <int MODE> ...
;     ...
;   f32x16 o[8] = {}; bf16x8 qr[8]; float lsum = 0.f;
;   const bf16* Qw = Qb + (long)(g * 32 + r32) * 128 + hi * 8;
; #pragma unroll
;   for (int d0 = 0; d0 < 8; ++d0) qr[d0] = St::ld8(Qw + d0 * 16);
;   const int vb0 = (int)(uintptr_t)V_lds + v_rd_base(lane) + 2 * kh * 4096;
;   const int krow = 32 * kh + r32;
;   typedef __attribute__((address_space(3))) unsigned lds_u32;
;   const int wu = __builtin_amdgcn_readfirstlane(wid);
;   long gk[2], gv[2];
; #pragma unroll
;   for (int c = 0; c < 2; ++c) { const int q = wu + 8 * c;
;     const int r = 4 * q + (lane >> 4), pch = lane & 15; gk[c] = (long)r * 128 + ((pch ^ (r & 7)) * 8);
;     const int st = 2 * q + (lane >> 5), kk = (st >> 2) * 8 + ((lane >> 2) & 7), k = (kk & ~0xC) | ((kk & 4) << 1) | ((kk & 8) >> 1), cc = (st & 3) * 32 + (lane & 3) * 8;
;     gv[c] = (long)k * 256 + cc; }
;     ...
;   const int NT = seq / KVBLK;
;   STAGE(0, 0); asm volatile("s_waitcnt vmcnt(0)" ::: "memory"); RAWBAR();
;   if (false) __builtin_amdgcn_s_setprio(1);
;   for (int j = 0; j < NT; ++j) {
;     const int buf = j & 1;
;     if (j + 1 < NT) { STAGE((j + 1) * KVBLK, buf ^ 1); }
;     const char* Kb = K_lds + buf * 16384;
;     f32x16 pe = {}, po = {};
; #pragma unroll
;     for (int d0 = 0; d0 < 8; d0 += 2) {
;       const bf16x8 k0 = *reinterpret_cast<const bf16x8*>(Kb + KSWZ(krow, (d0 * 16 + hi * 8) * 2));
;       const bf16x8 k1 = *reinterpret_cast<const bf16x8*>(Kb + KSWZ(krow, ((d0 + 1) * 16 + hi * 8) * 2));
;       pe = __builtin_amdgcn_mfma_f32_32x32x16_bf16(k0, qr[d0], pe, 0, 0, 0);
;       po = __builtin_amdgcn_mfma_f32_32x32x16_bf16(k1, qr[d0 + 1], po, 0, 0, 0); }
	v_add_u32_e32 v10, s41, v18
	v_readlane_b32 s84, v251, 28
	v_lshlrev_b64 v[0:1], 8, v[0:1]
	v_add3_u32 v10, v10, v17, v19
	v_lshl_or_b32 v2, v4, 1, v2
	v_readlane_b32 s85, v251, 29
	v_or_b32_e32 v0, v0, v15
	v_mov_b32_e32 v215, 0
	s_mov_b32 s25, 0
	v_add3_u32 v214, v10, v12, v20
	v_bitop3_b32 v223, v194, v5, 32 bitop3:0x36
	v_bitop3_b32 v222, v194, v5, 64 bitop3:0x36
	v_bitop3_b32 v221, v194, v5, s43 bitop3:0x36
	v_bitop3_b32 v220, v194, v5, s59 bitop3:0x36
	v_bitop3_b32 v219, v194, v5, s60 bitop3:0x36
	v_bitop3_b32 v218, v194, v5, s56 bitop3:0x36
	v_bitop3_b32 v217, v194, v5, s61 bitop3:0x36
	v_lshl_add_u64 v[198:199], s[84:85], 0, v[2:3]
	v_lshl_add_u64 v[200:201], s[84:85], 0, v[6:7]
	v_lshl_add_u64 v[202:203], s[6:7], 0, v[8:9]
	v_lshl_add_u64 v[204:205], s[6:7], 0, v[0:1]
	v_mov_b32_e32 v0, 0
	v_mov_b32_e32 v1, v215
	v_mov_b32_e32 v2, v215
	v_mov_b32_e32 v3, v215
	v_mov_b32_e32 v4, v215
	v_mov_b32_e32 v5, v215
	v_mov_b32_e32 v6, v215
	v_mov_b32_e32 v7, v215
	v_mov_b32_e32 v8, v215
	v_mov_b32_e32 v9, v215
	v_mov_b32_e32 v10, v215
	v_mov_b32_e32 v11, v215
	v_mov_b32_e32 v12, v215
	v_mov_b32_e32 v13, v215
	v_mov_b32_e32 v14, v215
	v_mov_b32_e32 v15, v215
	v_mov_b32_e32 v16, 0
	v_mov_b32_e32 v17, v215
	v_mov_b32_e32 v18, v215
	v_mov_b32_e32 v19, v215
	v_mov_b32_e32 v20, v215
	v_mov_b32_e32 v21, v215
	v_mov_b32_e32 v22, v215
	v_mov_b32_e32 v23, v215
	v_mov_b32_e32 v24, v215
	v_mov_b32_e32 v25, v215
	v_mov_b32_e32 v26, v215
	v_mov_b32_e32 v27, v215
	v_mov_b32_e32 v28, v215
	v_mov_b32_e32 v29, v215
	v_mov_b32_e32 v30, v215
	v_mov_b32_e32 v31, v215
	v_mov_b32_e32 v32, 0
	v_mov_b32_e32 v33, v215
	v_mov_b32_e32 v34, v215
	v_mov_b32_e32 v35, v215
	v_mov_b32_e32 v36, v215
	v_mov_b32_e32 v37, v215
	v_mov_b32_e32 v38, v215
	v_mov_b32_e32 v39, v215
	v_mov_b32_e32 v40, v215
	v_mov_b32_e32 v41, v215
	v_mov_b32_e32 v42, v215
	v_mov_b32_e32 v43, v215
	v_mov_b32_e32 v44, v215
	v_mov_b32_e32 v45, v215
	v_mov_b32_e32 v46, v215
	v_mov_b32_e32 v47, v215
	v_mov_b32_e32 v48, 0
	v_mov_b32_e32 v49, v215
	v_mov_b32_e32 v50, v215
	v_mov_b32_e32 v51, v215
	v_mov_b32_e32 v52, v215
	v_mov_b32_e32 v53, v215
	v_mov_b32_e32 v54, v215
	v_mov_b32_e32 v55, v215
	v_mov_b32_e32 v56, v215
	v_mov_b32_e32 v57, v215
	v_mov_b32_e32 v58, v215
	v_mov_b32_e32 v59, v215
	v_mov_b32_e32 v60, v215
	v_mov_b32_e32 v61, v215
	v_mov_b32_e32 v62, v215
	v_mov_b32_e32 v63, v215
	v_mov_b32_e32 v64, 0
	v_mov_b32_e32 v65, v215
	v_mov_b32_e32 v66, v215
	v_mov_b32_e32 v67, v215
	v_mov_b32_e32 v68, v215
	v_mov_b32_e32 v69, v215
	v_mov_b32_e32 v70, v215
	v_mov_b32_e32 v71, v215
	v_mov_b32_e32 v72, v215
	v_mov_b32_e32 v73, v215
	v_mov_b32_e32 v74, v215
	v_mov_b32_e32 v75, v215
	v_mov_b32_e32 v76, v215
	v_mov_b32_e32 v77, v215
	v_mov_b32_e32 v78, v215
	v_mov_b32_e32 v79, v215
	v_mov_b32_e32 v80, 0
	v_mov_b32_e32 v81, v215
	v_mov_b32_e32 v82, v215
	v_mov_b32_e32 v83, v215
	v_mov_b32_e32 v84, v215
	v_mov_b32_e32 v85, v215
	v_mov_b32_e32 v86, v215
	v_mov_b32_e32 v87, v215
	v_mov_b32_e32 v88, v215
	v_mov_b32_e32 v89, v215
	v_mov_b32_e32 v90, v215
	v_mov_b32_e32 v91, v215
	v_mov_b32_e32 v92, v215
	v_mov_b32_e32 v93, v215
	v_mov_b32_e32 v94, v215
	v_mov_b32_e32 v95, v215
	v_mov_b32_e32 v96, 0
	v_mov_b32_e32 v97, v215
	v_mov_b32_e32 v98, v215
	v_mov_b32_e32 v99, v215
	v_mov_b32_e32 v100, v215
	v_mov_b32_e32 v101, v215
	v_mov_b32_e32 v102, v215
	v_mov_b32_e32 v103, v215
	v_mov_b32_e32 v104, v215
	v_mov_b32_e32 v105, v215
	v_mov_b32_e32 v106, v215
	v_mov_b32_e32 v107, v215
	v_mov_b32_e32 v108, v215
	v_mov_b32_e32 v109, v215
	v_mov_b32_e32 v110, v215
	v_mov_b32_e32 v111, v215
	v_mov_b32_e32 v112, 0
	v_mov_b32_e32 v113, v215
	v_mov_b32_e32 v114, v215
	v_mov_b32_e32 v115, v215
	v_mov_b32_e32 v116, v215
	v_mov_b32_e32 v117, v215
	v_mov_b32_e32 v118, v215
	v_mov_b32_e32 v119, v215
	v_mov_b32_e32 v120, v215
	v_mov_b32_e32 v121, v215
	v_mov_b32_e32 v122, v215
	v_mov_b32_e32 v123, v215
	v_mov_b32_e32 v124, v215
	v_mov_b32_e32 v125, v215
	v_mov_b32_e32 v126, v215
	v_mov_b32_e32 v127, v215
	v_readlane_b32 s86, v251, 30
	v_readlane_b32 s87, v251, 31
	s_waitcnt vmcnt(0)
	v_subrev_u32_e32 v220, s6, v202
	v_subrev_u32_e32 v219, s6, v204
	v_subrev_u32_e32 v218, s84, v198
	v_subrev_u32_e32 v217, s84, v200
	v_add_u32_e32 v242, 0x100, v218
	v_add_u32_e32 v243, 0x100, v217
	s_add_u32 s86, s6, s26
	s_addc_u32 s87, s7, s27
	s_add_u32 s86, s86, 0x4000
	s_addc_u32 s87, s87, 0
	s_add_u32 s2, s84, s26
	s_addc_u32 s3, s85, s27
	s_add_u32 s2, s2, s12
	s_addc_u32 s3, s3, s13
	v_add_u32_e32 v225, v216, v225
	v_add_u32_e32 v223, v216, v223
	v_add_u32_e32 v222, v216, v222
	v_add_u32_e32 v221, v216, v221
	ds_read_b128 v[226:229], v225 offset:0
	ds_read_b128 v[230:233], v223 offset:0
	s_waitcnt lgkmcnt(0)
	v_mfma_f32_32x32x16_bf16 v[144:159], v[226:229], v[188:191], 0
	v_mfma_f32_32x32x16_bf16 v[144:159], v[230:233], v[184:187], v[144:159]
	ds_read_b128 v[226:229], v222 offset:0
	ds_read_b128 v[230:233], v221 offset:0
	s_waitcnt lgkmcnt(0)
	v_mfma_f32_32x32x16_bf16 v[144:159], v[226:229], v[180:183], v[144:159]
	v_mfma_f32_32x32x16_bf16 v[144:159], v[230:233], v[176:179], v[144:159]
	ds_read_b128 v[226:229], v225 offset:128
	ds_read_b128 v[230:233], v223 offset:128
	s_waitcnt lgkmcnt(0)
	v_mfma_f32_32x32x16_bf16 v[144:159], v[226:229], v[172:175], v[144:159]
	v_mfma_f32_32x32x16_bf16 v[144:159], v[230:233], v[168:171], v[144:159]
	ds_read_b128 v[226:229], v222 offset:128
	ds_read_b128 v[230:233], v221 offset:128
	s_waitcnt lgkmcnt(0)
	v_mfma_f32_32x32x16_bf16 v[144:159], v[226:229], v[164:167], v[144:159]
	v_mfma_f32_32x32x16_bf16 v[144:159], v[230:233], v[160:163], v[144:159]
	s_mov_b32 s84, 0
	s_barrier
	s_cmp_lt_u32 s24, 0x1000
	s_cbranch_scc0 .LattnBpre_m0
; #define SBAR() __builtin_amdgcn_sched_barrier(0)
; #define PVR(S, DA, DB, vbase) do { S[0] = tr_read<v_rd_off(DA, 0, 0)>(vbase); S[1] = tr_read<v_rd_off(DA, 0, 1)>(vbase); S[2] = tr_read<v_rd_off(DB, 0, 0)>(vbase); S[3] = tr_read<v_rd_off(DB, 0, 1)>(vbase); \
;     S[4] = tr_read<v_rd_off(DA, 1, 0)>(vbase); S[5] = tr_read<v_rd_off(DA, 1, 1)>(vbase); S[6] = tr_read<v_rd_off(DB, 1, 0)>(vbase); S[7] = tr_read<v_rd_off(DB, 1, 1)>(vbase); } while (0)
; #define RAWBAR() do { asm volatile("s_waitcnt lgkmcnt(0)" ::: "memory"); __builtin_amdgcn_s_barrier(); asm volatile("" ::: "memory"); } while (0)
; #define RAWBAR() do { asm volatile("s_waitcnt lgkmcnt(0)" ::: "memory"); __builtin_amdgcn_s_barrier(); asm volatile("" ::: "memory"); } while (0)
; #define RAWBAR() do { asm volatile("s_waitcnt lgkmcnt(0)" ::: "memory"); __builtin_amdgcn_s_barrier(); asm volatile("" ::: "memory"); } while (0)
; #define RAWBAR() do { asm volatile("s_waitcnt lgkmcnt(0)" ::: "memory"); __builtin_amdgcn_s_barrier(); asm volatile("" ::: "memory"); } while (0)
; #define RAWBAR() do { asm volatile("s_waitcnt lgkmcnt(0)" ::: "memory"); __builtin_amdgcn_s_barrier(); asm volatile("" ::: "memory"); } while (0)
; template <int MODE> ...
;     ...
;   for (int j = 0; j < NT; ++j) {
;     const int buf = j & 1;
;     if (j + 1 < NT) { STAGE((j + 1) * KVBLK, buf ^ 1); }
;     const char* Kb = K_lds + buf * 16384;
;     f32x16 pe = {}, po = {};
; #pragma unroll
;     for (int d0 = 0; d0 < 8; d0 += 2) {
;       const bf16x8 k0 = *reinterpret_cast<const bf16x8*>(Kb + KSWZ(krow, (d0 * 16 + hi * 8) * 2));
;       const bf16x8 k1 = *reinterpret_cast<const bf16x8*>(Kb + KSWZ(krow, ((d0 + 1) * 16 + hi * 8) * 2));
;       pe = __builtin_amdgcn_mfma_f32_32x32x16_bf16(k0, qr[d0], pe, 0, 0, 0);
;       po = __builtin_amdgcn_mfma_f32_32x32x16_bf16(k1, qr[d0 + 1], po, 0, 0, 0); }
;     const int vo = vb0 + buf * 32768;
;     s16x4 R0_[8], R1_[8];
;     PVR(R0_, 0, 1, vo);
;     f32x16 p;
; #pragma unroll
;     for (int r = 0; r < 16; ++r) p[r] = __builtin_amdgcn_exp2f(fmaf(pe[r] + po[r], C, negMc));
;     float ps = 0.f;
; #pragma unroll
;     for (int r = 0; r < 16; ++r) ps += p[r];
;     lsum += ps;
;     const bf16x8 own0 = pk8(p, 0), own1 = pk8(p, 8);
;     SBAR();
;     PV_TAIL4(o, vo, vo + 16384, own0, own1);
;     asm volatile("s_waitcnt vmcnt(0)" ::: "memory");
;     RAWBAR();
;   }
.LBB0_1019:
	ds_read_b128 v[226:229], v225 offset:16384
	ds_read_b128 v[230:233], v223 offset:16384
	ds_read_b128 v[234:237], v222 offset:16384
	ds_read_b128 v[238:241], v221 offset:16384
	s_mov_b32 m0, s24
	s_nop 0
	global_load_lds_dwordx4 v220, s[86:87]
	s_add_i32 m0, s24, 0x2000
	s_nop 0
	global_load_lds_dwordx4 v219, s[86:87]
	v_fmamk_f32 v144, v144, 0x3e0293ee, v208
	v_fmamk_f32 v145, v145, 0x3e0293ee, v208
	v_fmamk_f32 v146, v146, 0x3e0293ee, v208
	v_fmamk_f32 v147, v147, 0x3e0293ee, v208
	v_exp_f32_e32 v144, v144
	v_exp_f32_e32 v145, v145
	v_exp_f32_e32 v146, v146
	v_exp_f32_e32 v147, v147
	s_waitcnt lgkmcnt(2)
	v_mfma_f32_32x32x16_bf16 v[128:143], v[226:229], v[188:191], 0
	v_mfma_f32_32x32x16_bf16 v[128:143], v[230:233], v[184:187], v[128:143]
	ds_read_b128 v[226:229], v225 offset:16512
	ds_read_b128 v[230:233], v223 offset:16512
	v_fmamk_f32 v148, v148, 0x3e0293ee, v208
	v_fmamk_f32 v149, v149, 0x3e0293ee, v208
	v_fmamk_f32 v150, v150, 0x3e0293ee, v208
	v_fmamk_f32 v151, v151, 0x3e0293ee, v208
	v_exp_f32_e32 v148, v148
	v_exp_f32_e32 v149, v149
	v_exp_f32_e32 v150, v150
	v_exp_f32_e32 v151, v151
	v_add_f32_e32 v246, v144, v145
	v_add_f32_e32 v246, v146, v246
	v_add_f32_e32 v246, v147, v246
	s_waitcnt lgkmcnt(2)
	v_mfma_f32_32x32x16_bf16 v[128:143], v[234:237], v[180:183], v[128:143]
	v_mfma_f32_32x32x16_bf16 v[128:143], v[238:241], v[176:179], v[128:143]
	ds_read_b128 v[234:237], v222 offset:16512
	ds_read_b128 v[238:241], v221 offset:16512
	v_fmamk_f32 v152, v152, 0x3e0293ee, v208
	v_fmamk_f32 v153, v153, 0x3e0293ee, v208
	v_fmamk_f32 v154, v154, 0x3e0293ee, v208
	v_fmamk_f32 v155, v155, 0x3e0293ee, v208
	v_exp_f32_e32 v152, v152
	v_exp_f32_e32 v153, v153
	v_exp_f32_e32 v154, v154
	v_exp_f32_e32 v155, v155
	v_add_f32_e32 v246, v148, v246
	v_add_f32_e32 v246, v149, v246
	v_add_f32_e32 v246, v150, v246
	v_add_f32_e32 v246, v151, v246
	s_waitcnt lgkmcnt(2)
	v_mfma_f32_32x32x16_bf16 v[128:143], v[226:229], v[172:175], v[128:143]
	v_mfma_f32_32x32x16_bf16 v[128:143], v[230:233], v[168:171], v[128:143]
	v_fmamk_f32 v156, v156, 0x3e0293ee, v208
	v_fmamk_f32 v157, v157, 0x3e0293ee, v208
	v_fmamk_f32 v158, v158, 0x3e0293ee, v208
	v_fmamk_f32 v159, v159, 0x3e0293ee, v208
	v_exp_f32_e32 v156, v156
	v_exp_f32_e32 v157, v157
	v_exp_f32_e32 v158, v158
	v_exp_f32_e32 v159, v159
	v_add_f32_e32 v246, v152, v246
	v_add_f32_e32 v246, v153, v246
	v_add_f32_e32 v246, v154, v246
	v_add_f32_e32 v246, v155, v246
	v_cvt_pk_bf16_f32 v226, v144, v145
	v_cvt_pk_bf16_f32 v227, v146, v147
	v_cvt_pk_bf16_f32 v228, v148, v149
	v_cvt_pk_bf16_f32 v229, v150, v151
	s_waitcnt lgkmcnt(0)
	v_mfma_f32_32x32x16_bf16 v[128:143], v[234:237], v[164:167], v[128:143]
	v_mfma_f32_32x32x16_bf16 v[128:143], v[238:241], v[160:163], v[128:143]
	v_add_u32_e32 v245, s84, v214
	s_add_i32 s85, s84, 0x8000
	s_cmp_eq_u32 s85, 0x18000
	s_cselect_b32 s85, 0, s85
	ds_read_b64_tr_b16 v[234:235], v245 offset:0
	ds_read_b64_tr_b16 v[236:237], v245 offset:2048
	ds_read_b64_tr_b16 v[238:239], v245 offset:512
	ds_read_b64_tr_b16 v[240:241], v245 offset:2560
	v_permlane32_swap_b32_e32 v226, v228
	v_permlane32_swap_b32_e32 v227, v229
	ds_read_b64_tr_b16 v[144:145], v245 offset:4096
	ds_read_b64_tr_b16 v[146:147], v245 offset:6144
	ds_read_b64_tr_b16 v[148:149], v245 offset:4608
	ds_read_b64_tr_b16 v[150:151], v245 offset:6656
	v_add_f32_e32 v246, v156, v246
	v_add_f32_e32 v246, v157, v246
	v_add_f32_e32 v246, v158, v246
	v_add_f32_e32 v246, v159, v246
	v_cvt_pk_bf16_f32 v230, v152, v153
	v_cvt_pk_bf16_f32 v231, v154, v155
	v_cvt_pk_bf16_f32 v232, v156, v157
	v_cvt_pk_bf16_f32 v233, v158, v159
	v_add_f32_e32 v215, v215, v246
	ds_read_b64_tr_b16 v[152:153], v245 offset:1024
	ds_read_b64_tr_b16 v[154:155], v245 offset:3072
	ds_read_b64_tr_b16 v[156:157], v245 offset:1536
	ds_read_b64_tr_b16 v[158:159], v245 offset:3584
	v_permlane32_swap_b32_e32 v230, v232
	v_permlane32_swap_b32_e32 v231, v233
	s_waitcnt lgkmcnt(8)
	v_mfma_f32_32x32x16_bf16 v[112:127], v[226:229], v[234:237], v[112:127]
	v_mfma_f32_32x32x16_bf16 v[96:111], v[226:229], v[238:241], v[96:111]
	ds_read_b64_tr_b16 v[234:235], v245 offset:5120
	ds_read_b64_tr_b16 v[236:237], v245 offset:7168
	ds_read_b64_tr_b16 v[238:239], v245 offset:5632
	ds_read_b64_tr_b16 v[240:241], v245 offset:7680
	s_add_i32 s41, s85, s24
	s_add_i32 m0, s41, 0x8000
	s_nop 0
	global_load_lds_dwordx4 v218, s[2:3]
	s_waitcnt lgkmcnt(8)
	v_mfma_f32_32x32x16_bf16 v[112:127], v[230:233], v[144:147], v[112:127]
	v_mfma_f32_32x32x16_bf16 v[96:111], v[230:233], v[148:151], v[96:111]
	ds_read_b64_tr_b16 v[144:145], v245 offset:16384
	ds_read_b64_tr_b16 v[146:147], v245 offset:18432
	ds_read_b64_tr_b16 v[148:149], v245 offset:16896
	ds_read_b64_tr_b16 v[150:151], v245 offset:18944
	s_add_i32 s41, s85, s24
	s_add_i32 m0, s41, 0xa000
	s_nop 0
	global_load_lds_dwordx4 v217, s[2:3]
	s_waitcnt lgkmcnt(8)
	v_mfma_f32_32x32x16_bf16 v[80:95], v[226:229], v[152:155], v[80:95]
	v_mfma_f32_32x32x16_bf16 v[64:79], v[226:229], v[156:159], v[64:79]
	ds_read_b64_tr_b16 v[152:153], v245 offset:20480
	ds_read_b64_tr_b16 v[154:155], v245 offset:22528
	ds_read_b64_tr_b16 v[156:157], v245 offset:20992
	ds_read_b64_tr_b16 v[158:159], v245 offset:23040
	s_add_i32 s41, s85, s24
	s_add_i32 m0, s41, 0xc000
	s_nop 0
	global_load_lds_dwordx4 v242, s[2:3]
	s_waitcnt lgkmcnt(8)
	v_mfma_f32_32x32x16_bf16 v[80:95], v[230:233], v[234:237], v[80:95]
	v_mfma_f32_32x32x16_bf16 v[64:79], v[230:233], v[238:241], v[64:79]
	ds_read_b64_tr_b16 v[234:235], v245 offset:17408
	ds_read_b64_tr_b16 v[236:237], v245 offset:19456
	ds_read_b64_tr_b16 v[238:239], v245 offset:17920
	ds_read_b64_tr_b16 v[240:241], v245 offset:19968
	s_add_i32 s41, s85, s24
	s_add_i32 m0, s41, 0xe000
	s_nop 0
	global_load_lds_dwordx4 v243, s[2:3]
	s_waitcnt lgkmcnt(8)
	v_mfma_f32_32x32x16_bf16 v[48:63], v[226:229], v[144:147], v[48:63]
	v_mfma_f32_32x32x16_bf16 v[32:47], v[226:229], v[148:151], v[32:47]
	ds_read_b64_tr_b16 v[144:145], v245 offset:21504
	ds_read_b64_tr_b16 v[146:147], v245 offset:23552
	ds_read_b64_tr_b16 v[148:149], v245 offset:22016
	ds_read_b64_tr_b16 v[150:151], v245 offset:24064
	s_waitcnt lgkmcnt(8)
	v_mfma_f32_32x32x16_bf16 v[48:63], v[230:233], v[152:155], v[48:63]
	v_mfma_f32_32x32x16_bf16 v[32:47], v[230:233], v[156:159], v[32:47]
	s_waitcnt lgkmcnt(0)
	v_mfma_f32_32x32x16_bf16 v[16:31], v[226:229], v[234:237], v[16:31]
	s_waitcnt vmcnt(0)
	s_barrier
; #define SBAR() __builtin_amdgcn_sched_barrier(0)
; #define PVR(S, DA, DB, vbase) do { S[0] = tr_read<v_rd_off(DA, 0, 0)>(vbase); S[1] = tr_read<v_rd_off(DA, 0, 1)>(vbase); S[2] = tr_read<v_rd_off(DB, 0, 0)>(vbase); S[3] = tr_read<v_rd_off(DB, 0, 1)>(vbase); \
;     S[4] = tr_read<v_rd_off(DA, 1, 0)>(vbase); S[5] = tr_read<v_rd_off(DA, 1, 1)>(vbase); S[6] = tr_read<v_rd_off(DB, 1, 0)>(vbase); S[7] = tr_read<v_rd_off(DB, 1, 1)>(vbase); } while (0)
; #define RAWBAR() do { asm volatile("s_waitcnt lgkmcnt(0)" ::: "memory"); __builtin_amdgcn_s_barrier(); asm volatile("" ::: "memory"); } while (0)
; #define RAWBAR() do { asm volatile("s_waitcnt lgkmcnt(0)" ::: "memory"); __builtin_amdgcn_s_barrier(); asm volatile("" ::: "memory"); } while (0)
; #define RAWBAR() do { asm volatile("s_waitcnt lgkmcnt(0)" ::: "memory"); __builtin_amdgcn_s_barrier(); asm volatile("" ::: "memory"); } while (0)
; #define RAWBAR() do { asm volatile("s_waitcnt lgkmcnt(0)" ::: "memory"); __builtin_amdgcn_s_barrier(); asm volatile("" ::: "memory"); } while (0)
; #define RAWBAR() do { asm volatile("s_waitcnt lgkmcnt(0)" ::: "memory"); __builtin_amdgcn_s_barrier(); asm volatile("" ::: "memory"); } while (0)
; template <int MODE> ...
;     ...
;   for (int j = 0; j < NT; ++j) {
;     const int buf = j & 1;
;     if (j + 1 < NT) { STAGE((j + 1) * KVBLK, buf ^ 1); }
;     const char* Kb = K_lds + buf * 16384;
;     f32x16 pe = {}, po = {};
; #pragma unroll
;     for (int d0 = 0; d0 < 8; d0 += 2) {
;       const bf16x8 k0 = *reinterpret_cast<const bf16x8*>(Kb + KSWZ(krow, (d0 * 16 + hi * 8) * 2));
;       const bf16x8 k1 = *reinterpret_cast<const bf16x8*>(Kb + KSWZ(krow, ((d0 + 1) * 16 + hi * 8) * 2));
;       pe = __builtin_amdgcn_mfma_f32_32x32x16_bf16(k0, qr[d0], pe, 0, 0, 0);
;       po = __builtin_amdgcn_mfma_f32_32x32x16_bf16(k1, qr[d0 + 1], po, 0, 0, 0); }
;     const int vo = vb0 + buf * 32768;
;     s16x4 R0_[8], R1_[8];
;     PVR(R0_, 0, 1, vo);
;     f32x16 p;
; #pragma unroll
;     for (int r = 0; r < 16; ++r) p[r] = __builtin_amdgcn_exp2f(fmaf(pe[r] + po[r], C, negMc));
;     float ps = 0.f;
; #pragma unroll
;     for (int r = 0; r < 16; ++r) ps += p[r];
;     lsum += ps;
;     const bf16x8 own0 = pk8(p, 0), own1 = pk8(p, 8);
;     SBAR();
;     PV_TAIL4(o, vo, vo + 16384, own0, own1);
;     asm volatile("s_waitcnt vmcnt(0)" ::: "memory");
;     RAWBAR();
;   }
	s_add_u32 s86, s86, 0x4000
	s_addc_u32 s87, s87, 0
	s_add_u32 s2, s2, 0x8000
	s_addc_u32 s3, s3, 0
	v_mfma_f32_32x32x16_bf16 v[0:15], v[226:229], v[238:241], v[0:15]
	v_mfma_f32_32x32x16_bf16 v[16:31], v[230:233], v[144:147], v[16:31]
	v_mfma_f32_32x32x16_bf16 v[0:15], v[230:233], v[148:151], v[0:15]
	s_add_i32 s84, s84, 0x8000
	s_cmp_eq_u32 s84, 0x18000
	s_cselect_b32 s84, 0, s84
	ds_read_b128 v[226:229], v225 offset:0
	ds_read_b128 v[230:233], v223 offset:0
	ds_read_b128 v[234:237], v222 offset:0
	ds_read_b128 v[238:241], v221 offset:0
	s_add_i32 m0, s24, 0x4000
	s_nop 0
	global_load_lds_dwordx4 v220, s[86:87]
	s_add_i32 m0, s24, 0x6000
	s_nop 0
	global_load_lds_dwordx4 v219, s[86:87]
	v_fmamk_f32 v128, v128, 0x3e0293ee, v208
	v_fmamk_f32 v129, v129, 0x3e0293ee, v208
	v_fmamk_f32 v130, v130, 0x3e0293ee, v208
	v_fmamk_f32 v131, v131, 0x3e0293ee, v208
	v_exp_f32_e32 v128, v128
	v_exp_f32_e32 v129, v129
	v_exp_f32_e32 v130, v130
	v_exp_f32_e32 v131, v131
	s_waitcnt lgkmcnt(2)
	v_mfma_f32_32x32x16_bf16 v[144:159], v[226:229], v[188:191], 0
	v_mfma_f32_32x32x16_bf16 v[144:159], v[230:233], v[184:187], v[144:159]
	ds_read_b128 v[226:229], v225 offset:128
	ds_read_b128 v[230:233], v223 offset:128
	v_fmamk_f32 v132, v132, 0x3e0293ee, v208
	v_fmamk_f32 v133, v133, 0x3e0293ee, v208
	v_fmamk_f32 v134, v134, 0x3e0293ee, v208
	v_fmamk_f32 v135, v135, 0x3e0293ee, v208
	v_exp_f32_e32 v132, v132
	v_exp_f32_e32 v133, v133
	v_exp_f32_e32 v134, v134
	v_exp_f32_e32 v135, v135
	v_add_f32_e32 v246, v128, v129
	v_add_f32_e32 v246, v130, v246
	v_add_f32_e32 v246, v131, v246
	s_waitcnt lgkmcnt(2)
	v_mfma_f32_32x32x16_bf16 v[144:159], v[234:237], v[180:183], v[144:159]
	v_mfma_f32_32x32x16_bf16 v[144:159], v[238:241], v[176:179], v[144:159]
	ds_read_b128 v[234:237], v222 offset:128
	ds_read_b128 v[238:241], v221 offset:128
	v_fmamk_f32 v136, v136, 0x3e0293ee, v208
	v_fmamk_f32 v137, v137, 0x3e0293ee, v208
	v_fmamk_f32 v138, v138, 0x3e0293ee, v208
	v_fmamk_f32 v139, v139, 0x3e0293ee, v208
	v_exp_f32_e32 v136, v136
	v_exp_f32_e32 v137, v137
	v_exp_f32_e32 v138, v138
	v_exp_f32_e32 v139, v139
	v_add_f32_e32 v246, v132, v246
	v_add_f32_e32 v246, v133, v246
	v_add_f32_e32 v246, v134, v246
	v_add_f32_e32 v246, v135, v246
	s_waitcnt lgkmcnt(2)
	v_mfma_f32_32x32x16_bf16 v[144:159], v[226:229], v[172:175], v[144:159]
	v_mfma_f32_32x32x16_bf16 v[144:159], v[230:233], v[168:171], v[144:159]
	v_fmamk_f32 v140, v140, 0x3e0293ee, v208
	v_fmamk_f32 v141, v141, 0x3e0293ee, v208
	v_fmamk_f32 v142, v142, 0x3e0293ee, v208
	v_fmamk_f32 v143, v143, 0x3e0293ee, v208
	v_exp_f32_e32 v140, v140
	v_exp_f32_e32 v141, v141
	v_exp_f32_e32 v142, v142
	v_exp_f32_e32 v143, v143
	v_add_f32_e32 v246, v136, v246
	v_add_f32_e32 v246, v137, v246
	v_add_f32_e32 v246, v138, v246
	v_add_f32_e32 v246, v139, v246
	v_cvt_pk_bf16_f32 v226, v128, v129
	v_cvt_pk_bf16_f32 v227, v130, v131
	v_cvt_pk_bf16_f32 v228, v132, v133
	v_cvt_pk_bf16_f32 v229, v134, v135
	s_waitcnt lgkmcnt(0)
	v_mfma_f32_32x32x16_bf16 v[144:159], v[234:237], v[164:167], v[144:159]
	v_mfma_f32_32x32x16_bf16 v[144:159], v[238:241], v[160:163], v[144:159]
	v_add_u32_e32 v245, s84, v214
	s_add_i32 s85, s84, 0x8000
	s_cmp_eq_u32 s85, 0x18000
	s_cselect_b32 s85, 0, s85
	ds_read_b64_tr_b16 v[234:235], v245 offset:0
	ds_read_b64_tr_b16 v[236:237], v245 offset:2048
	ds_read_b64_tr_b16 v[238:239], v245 offset:512
	ds_read_b64_tr_b16 v[240:241], v245 offset:2560
	v_permlane32_swap_b32_e32 v226, v228
	v_permlane32_swap_b32_e32 v227, v229
	ds_read_b64_tr_b16 v[128:129], v245 offset:4096
	ds_read_b64_tr_b16 v[130:131], v245 offset:6144
	ds_read_b64_tr_b16 v[132:133], v245 offset:4608
	ds_read_b64_tr_b16 v[134:135], v245 offset:6656
	v_add_f32_e32 v246, v140, v246
	v_add_f32_e32 v246, v141, v246
	v_add_f32_e32 v246, v142, v246
	v_add_f32_e32 v246, v143, v246
	v_cvt_pk_bf16_f32 v230, v136, v137
	v_cvt_pk_bf16_f32 v231, v138, v139
	v_cvt_pk_bf16_f32 v232, v140, v141
	v_cvt_pk_bf16_f32 v233, v142, v143
	v_add_f32_e32 v215, v215, v246
	ds_read_b64_tr_b16 v[136:137], v245 offset:1024
	ds_read_b64_tr_b16 v[138:139], v245 offset:3072
	ds_read_b64_tr_b16 v[140:141], v245 offset:1536
	ds_read_b64_tr_b16 v[142:143], v245 offset:3584
	v_permlane32_swap_b32_e32 v230, v232
	v_permlane32_swap_b32_e32 v231, v233
	s_waitcnt lgkmcnt(8)
	v_mfma_f32_32x32x16_bf16 v[112:127], v[226:229], v[234:237], v[112:127]
	v_mfma_f32_32x32x16_bf16 v[96:111], v[226:229], v[238:241], v[96:111]
	ds_read_b64_tr_b16 v[234:235], v245 offset:5120
	ds_read_b64_tr_b16 v[236:237], v245 offset:7168
	ds_read_b64_tr_b16 v[238:239], v245 offset:5632
	ds_read_b64_tr_b16 v[240:241], v245 offset:7680
	s_add_i32 s41, s85, s24
	s_add_i32 m0, s41, 0x8000
	s_nop 0
	global_load_lds_dwordx4 v218, s[2:3]
	s_waitcnt lgkmcnt(8)
	v_mfma_f32_32x32x16_bf16 v[112:127], v[230:233], v[128:131], v[112:127]
	v_mfma_f32_32x32x16_bf16 v[96:111], v[230:233], v[132:135], v[96:111]
	ds_read_b64_tr_b16 v[128:129], v245 offset:16384
	ds_read_b64_tr_b16 v[130:131], v245 offset:18432
	ds_read_b64_tr_b16 v[132:133], v245 offset:16896
	ds_read_b64_tr_b16 v[134:135], v245 offset:18944
	s_add_i32 s41, s85, s24
	s_add_i32 m0, s41, 0xa000
	s_nop 0
	global_load_lds_dwordx4 v217, s[2:3]
	s_waitcnt lgkmcnt(8)
	v_mfma_f32_32x32x16_bf16 v[80:95], v[226:229], v[136:139], v[80:95]
	v_mfma_f32_32x32x16_bf16 v[64:79], v[226:229], v[140:143], v[64:79]
	ds_read_b64_tr_b16 v[136:137], v245 offset:20480
	ds_read_b64_tr_b16 v[138:139], v245 offset:22528
	ds_read_b64_tr_b16 v[140:141], v245 offset:20992
	ds_read_b64_tr_b16 v[142:143], v245 offset:23040
	s_add_i32 s41, s85, s24
	s_add_i32 m0, s41, 0xc000
	s_nop 0
	global_load_lds_dwordx4 v242, s[2:3]
	s_waitcnt lgkmcnt(8)
	v_mfma_f32_32x32x16_bf16 v[80:95], v[230:233], v[234:237], v[80:95]
	v_mfma_f32_32x32x16_bf16 v[64:79], v[230:233], v[238:241], v[64:79]
	ds_read_b64_tr_b16 v[234:235], v245 offset:17408
	ds_read_b64_tr_b16 v[236:237], v245 offset:19456
	ds_read_b64_tr_b16 v[238:239], v245 offset:17920
	ds_read_b64_tr_b16 v[240:241], v245 offset:19968
	s_add_i32 s41, s85, s24
	s_add_i32 m0, s41, 0xe000
	s_nop 0
	global_load_lds_dwordx4 v243, s[2:3]
	s_waitcnt lgkmcnt(8)
	v_mfma_f32_32x32x16_bf16 v[48:63], v[226:229], v[128:131], v[48:63]
	v_mfma_f32_32x32x16_bf16 v[32:47], v[226:229], v[132:135], v[32:47]
	ds_read_b64_tr_b16 v[128:129], v245 offset:21504
	ds_read_b64_tr_b16 v[130:131], v245 offset:23552
	ds_read_b64_tr_b16 v[132:133], v245 offset:22016
	ds_read_b64_tr_b16 v[134:135], v245 offset:24064
	s_waitcnt lgkmcnt(8)
	v_mfma_f32_32x32x16_bf16 v[48:63], v[230:233], v[136:139], v[48:63]
	v_mfma_f32_32x32x16_bf16 v[32:47], v[230:233], v[140:143], v[32:47]
	s_waitcnt lgkmcnt(0)
	v_mfma_f32_32x32x16_bf16 v[16:31], v[226:229], v[234:237], v[16:31]
	s_waitcnt vmcnt(0)
	s_barrier
; #define SBAR() __builtin_amdgcn_sched_barrier(0)
; #define PVR(S, DA, DB, vbase) do { S[0] = tr_read<v_rd_off(DA, 0, 0)>(vbase); S[1] = tr_read<v_rd_off(DA, 0, 1)>(vbase); S[2] = tr_read<v_rd_off(DB, 0, 0)>(vbase); S[3] = tr_read<v_rd_off(DB, 0, 1)>(vbase); \
;     S[4] = tr_read<v_rd_off(DA, 1, 0)>(vbase); S[5] = tr_read<v_rd_off(DA, 1, 1)>(vbase); S[6] = tr_read<v_rd_off(DB, 1, 0)>(vbase); S[7] = tr_read<v_rd_off(DB, 1, 1)>(vbase); } while (0)
; #define RAWBAR() do { asm volatile("s_waitcnt lgkmcnt(0)" ::: "memory"); __builtin_amdgcn_s_barrier(); asm volatile("" ::: "memory"); } while (0)
; #define RAWBAR() do { asm volatile("s_waitcnt lgkmcnt(0)" ::: "memory"); __builtin_amdgcn_s_barrier(); asm volatile("" ::: "memory"); } while (0)
; #define RAWBAR() do { asm volatile("s_waitcnt lgkmcnt(0)" ::: "memory"); __builtin_amdgcn_s_barrier(); asm volatile("" ::: "memory"); } while (0)
; #define RAWBAR() do { asm volatile("s_waitcnt lgkmcnt(0)" ::: "memory"); __builtin_amdgcn_s_barrier(); asm volatile("" ::: "memory"); } while (0)
; #define RAWBAR() do { asm volatile("s_waitcnt lgkmcnt(0)" ::: "memory"); __builtin_amdgcn_s_barrier(); asm volatile("" ::: "memory"); } while (0)
; template <int MODE> ...
;     ...
;   for (int j = 0; j < NT; ++j) {
;     const int buf = j & 1;
;     if (j + 1 < NT) { STAGE((j + 1) * KVBLK, buf ^ 1); }
;     const char* Kb = K_lds + buf * 16384;
;     f32x16 pe = {}, po = {};
; #pragma unroll
;     for (int d0 = 0; d0 < 8; d0 += 2) {
;       const bf16x8 k0 = *reinterpret_cast<const bf16x8*>(Kb + KSWZ(krow, (d0 * 16 + hi * 8) * 2));
;       const bf16x8 k1 = *reinterpret_cast<const bf16x8*>(Kb + KSWZ(krow, ((d0 + 1) * 16 + hi * 8) * 2));
;       pe = __builtin_amdgcn_mfma_f32_32x32x16_bf16(k0, qr[d0], pe, 0, 0, 0);
;       po = __builtin_amdgcn_mfma_f32_32x32x16_bf16(k1, qr[d0 + 1], po, 0, 0, 0); }
;     const int vo = vb0 + buf * 32768;
;     s16x4 R0_[8], R1_[8];
;     PVR(R0_, 0, 1, vo);
;     f32x16 p;
; #pragma unroll
;     for (int r = 0; r < 16; ++r) p[r] = __builtin_amdgcn_exp2f(fmaf(pe[r] + po[r], C, negMc));
;     float ps = 0.f;
; #pragma unroll
;     for (int r = 0; r < 16; ++r) ps += p[r];
;     lsum += ps;
;     const bf16x8 own0 = pk8(p, 0), own1 = pk8(p, 8);
;     SBAR();
;     PV_TAIL4(o, vo, vo + 16384, own0, own1);
;     asm volatile("s_waitcnt vmcnt(0)" ::: "memory");
;     RAWBAR();
;   }
	s_add_u32 s86, s86, 0x4000
	s_addc_u32 s87, s87, 0
	s_add_u32 s2, s2, 0x8000
	s_addc_u32 s3, s3, 0
	v_mfma_f32_32x32x16_bf16 v[0:15], v[226:229], v[238:241], v[0:15]
	v_mfma_f32_32x32x16_bf16 v[16:31], v[230:233], v[128:131], v[16:31]
	v_mfma_f32_32x32x16_bf16 v[0:15], v[230:233], v[132:135], v[0:15]
	s_add_i32 s84, s84, 0x8000
	s_cmp_eq_u32 s84, 0x18000
	s_cselect_b32 s84, 0, s84
	s_add_i32 s25, s25, 1
	s_cmpk_eq_i32 s25, 0x82
	s_cbranch_scc0 .LBB0_1019
	s_barrier
	s_branch .Lattn_join_m0
.LattnBpre_m0:
	s_mov_b32 m0, s24
	s_nop 0
	global_load_lds_dwordx4 v220, s[86:87]
	s_add_i32 m0, s24, 0x2000
	s_nop 0
	global_load_lds_dwordx4 v219, s[86:87]
	s_add_i32 s85, s84, 0x8000
	s_cmp_eq_u32 s85, 0x18000
	s_cselect_b32 s85, 0, s85
	s_add_i32 s41, s85, s24
	s_add_i32 m0, s41, 0x8000
	s_nop 0
	global_load_lds_dwordx4 v218, s[2:3]
	s_add_i32 s41, s85, s24
	s_add_i32 m0, s41, 0xa000
	s_nop 0
	global_load_lds_dwordx4 v217, s[2:3]
	s_add_i32 s41, s85, s24
	s_add_i32 m0, s41, 0xc000
	s_nop 0
	global_load_lds_dwordx4 v242, s[2:3]
	s_add_i32 s41, s85, s24
	s_add_i32 m0, s41, 0xe000
	s_nop 0
	global_load_lds_dwordx4 v243, s[2:3]
.LattnB_m0:
	ds_read_b128 v[226:229], v225 offset:16384
	ds_read_b128 v[230:233], v223 offset:16384
	ds_read_b128 v[234:237], v222 offset:16384
	ds_read_b128 v[238:241], v221 offset:16384
	v_fmamk_f32 v144, v144, 0x3e0293ee, v208
	v_fmamk_f32 v145, v145, 0x3e0293ee, v208
	v_fmamk_f32 v146, v146, 0x3e0293ee, v208
	v_fmamk_f32 v147, v147, 0x3e0293ee, v208
	v_exp_f32_e32 v144, v144
	v_exp_f32_e32 v145, v145
	v_exp_f32_e32 v146, v146
	v_exp_f32_e32 v147, v147
	s_waitcnt lgkmcnt(2)
	v_mfma_f32_32x32x16_bf16 v[128:143], v[226:229], v[188:191], 0
	v_mfma_f32_32x32x16_bf16 v[128:143], v[230:233], v[184:187], v[128:143]
	ds_read_b128 v[226:229], v225 offset:16512
	ds_read_b128 v[230:233], v223 offset:16512
	v_fmamk_f32 v148, v148, 0x3e0293ee, v208
	v_fmamk_f32 v149, v149, 0x3e0293ee, v208
	v_fmamk_f32 v150, v150, 0x3e0293ee, v208
	v_fmamk_f32 v151, v151, 0x3e0293ee, v208
	v_exp_f32_e32 v148, v148
	v_exp_f32_e32 v149, v149
	v_exp_f32_e32 v150, v150
	v_exp_f32_e32 v151, v151
	v_add_f32_e32 v246, v144, v145
	v_add_f32_e32 v246, v146, v246
	v_add_f32_e32 v246, v147, v246
	s_waitcnt lgkmcnt(2)
	v_mfma_f32_32x32x16_bf16 v[128:143], v[234:237], v[180:183], v[128:143]
	v_mfma_f32_32x32x16_bf16 v[128:143], v[238:241], v[176:179], v[128:143]
	ds_read_b128 v[234:237], v222 offset:16512
	ds_read_b128 v[238:241], v221 offset:16512
	v_fmamk_f32 v152, v152, 0x3e0293ee, v208
	v_fmamk_f32 v153, v153, 0x3e0293ee, v208
	v_fmamk_f32 v154, v154, 0x3e0293ee, v208
	v_fmamk_f32 v155, v155, 0x3e0293ee, v208
	v_exp_f32_e32 v152, v152
	v_exp_f32_e32 v153, v153
	v_exp_f32_e32 v154, v154
	v_exp_f32_e32 v155, v155
	v_add_f32_e32 v246, v148, v246
	v_add_f32_e32 v246, v149, v246
	v_add_f32_e32 v246, v150, v246
	v_add_f32_e32 v246, v151, v246
	s_waitcnt lgkmcnt(2)
	v_mfma_f32_32x32x16_bf16 v[128:143], v[226:229], v[172:175], v[128:143]
	v_mfma_f32_32x32x16_bf16 v[128:143], v[230:233], v[168:171], v[128:143]
	v_fmamk_f32 v156, v156, 0x3e0293ee, v208
	v_fmamk_f32 v157, v157, 0x3e0293ee, v208
	v_fmamk_f32 v158, v158, 0x3e0293ee, v208
	v_fmamk_f32 v159, v159, 0x3e0293ee, v208
	v_exp_f32_e32 v156, v156
	v_exp_f32_e32 v157, v157
	v_exp_f32_e32 v158, v158
	v_exp_f32_e32 v159, v159
	v_add_f32_e32 v246, v152, v246
	v_add_f32_e32 v246, v153, v246
	v_add_f32_e32 v246, v154, v246
	v_add_f32_e32 v246, v155, v246
	v_cvt_pk_bf16_f32 v226, v144, v145
	v_cvt_pk_bf16_f32 v227, v146, v147
	v_cvt_pk_bf16_f32 v228, v148, v149
	v_cvt_pk_bf16_f32 v229, v150, v151
	s_waitcnt lgkmcnt(0)
	v_mfma_f32_32x32x16_bf16 v[128:143], v[234:237], v[164:167], v[128:143]
	v_mfma_f32_32x32x16_bf16 v[128:143], v[238:241], v[160:163], v[128:143]
	s_waitcnt vmcnt(0)
	s_barrier
	s_add_u32 s86, s86, 0x4000
	s_addc_u32 s87, s87, 0
	s_add_u32 s2, s2, 0x8000
	s_addc_u32 s3, s3, 0
	s_add_i32 m0, s24, 0x4000
	s_nop 0
	global_load_lds_dwordx4 v220, s[86:87]
	s_add_i32 m0, s24, 0x6000
	s_nop 0
	global_load_lds_dwordx4 v219, s[86:87]
	v_add_u32_e32 v245, s84, v214
	s_sub_u32 s85, s84, 0x8000
	s_cmp_eq_u32 s84, 0
	s_cselect_b32 s85, 0x10000, s85
	ds_read_b64_tr_b16 v[234:235], v245 offset:0
	ds_read_b64_tr_b16 v[236:237], v245 offset:2048
	ds_read_b64_tr_b16 v[238:239], v245 offset:512
	ds_read_b64_tr_b16 v[240:241], v245 offset:2560
	v_permlane32_swap_b32_e32 v226, v228
	v_permlane32_swap_b32_e32 v227, v229
	ds_read_b64_tr_b16 v[144:145], v245 offset:4096
	ds_read_b64_tr_b16 v[146:147], v245 offset:6144
	ds_read_b64_tr_b16 v[148:149], v245 offset:4608
	ds_read_b64_tr_b16 v[150:151], v245 offset:6656
	v_add_f32_e32 v246, v156, v246
	v_add_f32_e32 v246, v157, v246
	v_add_f32_e32 v246, v158, v246
	v_add_f32_e32 v246, v159, v246
	v_cvt_pk_bf16_f32 v230, v152, v153
	v_cvt_pk_bf16_f32 v231, v154, v155
	v_cvt_pk_bf16_f32 v232, v156, v157
	v_cvt_pk_bf16_f32 v233, v158, v159
	v_add_f32_e32 v215, v215, v246
	ds_read_b64_tr_b16 v[152:153], v245 offset:1024
	ds_read_b64_tr_b16 v[154:155], v245 offset:3072
	ds_read_b64_tr_b16 v[156:157], v245 offset:1536
	ds_read_b64_tr_b16 v[158:159], v245 offset:3584
	v_permlane32_swap_b32_e32 v230, v232
	v_permlane32_swap_b32_e32 v231, v233
	s_waitcnt lgkmcnt(8)
	v_mfma_f32_32x32x16_bf16 v[112:127], v[226:229], v[234:237], v[112:127]
	v_mfma_f32_32x32x16_bf16 v[96:111], v[226:229], v[238:241], v[96:111]
	ds_read_b64_tr_b16 v[234:235], v245 offset:5120
	ds_read_b64_tr_b16 v[236:237], v245 offset:7168
	ds_read_b64_tr_b16 v[238:239], v245 offset:5632
	ds_read_b64_tr_b16 v[240:241], v245 offset:7680
	s_add_i32 s41, s85, s24
	s_add_i32 m0, s41, 0x8000
	s_nop 0
	global_load_lds_dwordx4 v218, s[2:3]
	s_waitcnt lgkmcnt(8)
; #define SBAR() __builtin_amdgcn_sched_barrier(0)
; #define PVR(S, DA, DB, vbase) do { S[0] = tr_read<v_rd_off(DA, 0, 0)>(vbase); S[1] = tr_read<v_rd_off(DA, 0, 1)>(vbase); S[2] = tr_read<v_rd_off(DB, 0, 0)>(vbase); S[3] = tr_read<v_rd_off(DB, 0, 1)>(vbase); \
;     S[4] = tr_read<v_rd_off(DA, 1, 0)>(vbase); S[5] = tr_read<v_rd_off(DA, 1, 1)>(vbase); S[6] = tr_read<v_rd_off(DB, 1, 0)>(vbase); S[7] = tr_read<v_rd_off(DB, 1, 1)>(vbase); } while (0)
; #define RAWBAR() do { asm volatile("s_waitcnt lgkmcnt(0)" ::: "memory"); __builtin_amdgcn_s_barrier(); asm volatile("" ::: "memory"); } while (0)
; #define RAWBAR() do { asm volatile("s_waitcnt lgkmcnt(0)" ::: "memory"); __builtin_amdgcn_s_barrier(); asm volatile("" ::: "memory"); } while (0)
; #define RAWBAR() do { asm volatile("s_waitcnt lgkmcnt(0)" ::: "memory"); __builtin_amdgcn_s_barrier(); asm volatile("" ::: "memory"); } while (0)
; #define RAWBAR() do { asm volatile("s_waitcnt lgkmcnt(0)" ::: "memory"); __builtin_amdgcn_s_barrier(); asm volatile("" ::: "memory"); } while (0)
; #define RAWBAR() do { asm volatile("s_waitcnt lgkmcnt(0)" ::: "memory"); __builtin_amdgcn_s_barrier(); asm volatile("" ::: "memory"); } while (0)
; template <int MODE> ...
;     ...
;   for (int j = 0; j < NT; ++j) {
;     const int buf = j & 1;
;     if (j + 1 < NT) { STAGE((j + 1) * KVBLK, buf ^ 1); }
;     const char* Kb = K_lds + buf * 16384;
;     f32x16 pe = {}, po = {};
; #pragma unroll
;     for (int d0 = 0; d0 < 8; d0 += 2) {
;       const bf16x8 k0 = *reinterpret_cast<const bf16x8*>(Kb + KSWZ(krow, (d0 * 16 + hi * 8) * 2));
;       const bf16x8 k1 = *reinterpret_cast<const bf16x8*>(Kb + KSWZ(krow, ((d0 + 1) * 16 + hi * 8) * 2));
;       pe = __builtin_amdgcn_mfma_f32_32x32x16_bf16(k0, qr[d0], pe, 0, 0, 0);
;       po = __builtin_amdgcn_mfma_f32_32x32x16_bf16(k1, qr[d0 + 1], po, 0, 0, 0); }
;     const int vo = vb0 + buf * 32768;
;     s16x4 R0_[8], R1_[8];
;     PVR(R0_, 0, 1, vo);
;     f32x16 p;
; #pragma unroll
;     for (int r = 0; r < 16; ++r) p[r] = __builtin_amdgcn_exp2f(fmaf(pe[r] + po[r], C, negMc));
;     float ps = 0.f;
; #pragma unroll
;     for (int r = 0; r < 16; ++r) ps += p[r];
;     lsum += ps;
;     const bf16x8 own0 = pk8(p, 0), own1 = pk8(p, 8);
;     SBAR();
;     PV_TAIL4(o, vo, vo + 16384, own0, own1);
;     asm volatile("s_waitcnt vmcnt(0)" ::: "memory");
;     RAWBAR();
;   }
	v_mfma_f32_32x32x16_bf16 v[112:127], v[230:233], v[144:147], v[112:127]
	v_mfma_f32_32x32x16_bf16 v[96:111], v[230:233], v[148:151], v[96:111]
	ds_read_b64_tr_b16 v[144:145], v245 offset:16384
	ds_read_b64_tr_b16 v[146:147], v245 offset:18432
	ds_read_b64_tr_b16 v[148:149], v245 offset:16896
	ds_read_b64_tr_b16 v[150:151], v245 offset:18944
	s_add_i32 s41, s85, s24
	s_add_i32 m0, s41, 0xa000
	s_nop 0
	global_load_lds_dwordx4 v217, s[2:3]
	s_waitcnt lgkmcnt(8)
	v_mfma_f32_32x32x16_bf16 v[80:95], v[226:229], v[152:155], v[80:95]
	v_mfma_f32_32x32x16_bf16 v[64:79], v[226:229], v[156:159], v[64:79]
	ds_read_b64_tr_b16 v[152:153], v245 offset:20480
	ds_read_b64_tr_b16 v[154:155], v245 offset:22528
	ds_read_b64_tr_b16 v[156:157], v245 offset:20992
	ds_read_b64_tr_b16 v[158:159], v245 offset:23040
	s_add_i32 s41, s85, s24
	s_add_i32 m0, s41, 0xc000
	s_nop 0
	global_load_lds_dwordx4 v242, s[2:3]
	s_waitcnt lgkmcnt(8)
	v_mfma_f32_32x32x16_bf16 v[80:95], v[230:233], v[234:237], v[80:95]
	v_mfma_f32_32x32x16_bf16 v[64:79], v[230:233], v[238:241], v[64:79]
	ds_read_b64_tr_b16 v[234:235], v245 offset:17408
	ds_read_b64_tr_b16 v[236:237], v245 offset:19456
	ds_read_b64_tr_b16 v[238:239], v245 offset:17920
	ds_read_b64_tr_b16 v[240:241], v245 offset:19968
	s_add_i32 s41, s85, s24
	s_add_i32 m0, s41, 0xe000
	s_nop 0
	global_load_lds_dwordx4 v243, s[2:3]
	s_waitcnt lgkmcnt(8)
	v_mfma_f32_32x32x16_bf16 v[48:63], v[226:229], v[144:147], v[48:63]
	v_mfma_f32_32x32x16_bf16 v[32:47], v[226:229], v[148:151], v[32:47]
	ds_read_b64_tr_b16 v[144:145], v245 offset:21504
	ds_read_b64_tr_b16 v[146:147], v245 offset:23552
	ds_read_b64_tr_b16 v[148:149], v245 offset:22016
	ds_read_b64_tr_b16 v[150:151], v245 offset:24064
	s_waitcnt lgkmcnt(8)
	v_mfma_f32_32x32x16_bf16 v[48:63], v[230:233], v[152:155], v[48:63]
	v_mfma_f32_32x32x16_bf16 v[32:47], v[230:233], v[156:159], v[32:47]
	s_waitcnt lgkmcnt(0)
	v_mfma_f32_32x32x16_bf16 v[16:31], v[226:229], v[234:237], v[16:31]
	v_mfma_f32_32x32x16_bf16 v[0:15], v[226:229], v[238:241], v[0:15]
	v_mfma_f32_32x32x16_bf16 v[16:31], v[230:233], v[144:147], v[16:31]
	v_mfma_f32_32x32x16_bf16 v[0:15], v[230:233], v[148:151], v[0:15]
	s_add_i32 s84, s84, 0x8000
	s_cmp_eq_u32 s84, 0x18000
	s_cselect_b32 s84, 0, s84
	ds_read_b128 v[226:229], v225 offset:0
	ds_read_b128 v[230:233], v223 offset:0
	ds_read_b128 v[234:237], v222 offset:0
	ds_read_b128 v[238:241], v221 offset:0
	v_fmamk_f32 v128, v128, 0x3e0293ee, v208
	v_fmamk_f32 v129, v129, 0x3e0293ee, v208
	v_fmamk_f32 v130, v130, 0x3e0293ee, v208
	v_fmamk_f32 v131, v131, 0x3e0293ee, v208
	v_exp_f32_e32 v128, v128
	v_exp_f32_e32 v129, v129
	v_exp_f32_e32 v130, v130
	v_exp_f32_e32 v131, v131
	s_waitcnt lgkmcnt(2)
	v_mfma_f32_32x32x16_bf16 v[144:159], v[226:229], v[188:191], 0
	v_mfma_f32_32x32x16_bf16 v[144:159], v[230:233], v[184:187], v[144:159]
	ds_read_b128 v[226:229], v225 offset:128
	ds_read_b128 v[230:233], v223 offset:128
	v_fmamk_f32 v132, v132, 0x3e0293ee, v208
	v_fmamk_f32 v133, v133, 0x3e0293ee, v208
	v_fmamk_f32 v134, v134, 0x3e0293ee, v208
	v_fmamk_f32 v135, v135, 0x3e0293ee, v208
	v_exp_f32_e32 v132, v132
	v_exp_f32_e32 v133, v133
	v_exp_f32_e32 v134, v134
	v_exp_f32_e32 v135, v135
	v_add_f32_e32 v246, v128, v129
	v_add_f32_e32 v246, v130, v246
	v_add_f32_e32 v246, v131, v246
	s_waitcnt lgkmcnt(2)
	v_mfma_f32_32x32x16_bf16 v[144:159], v[234:237], v[180:183], v[144:159]
	v_mfma_f32_32x32x16_bf16 v[144:159], v[238:241], v[176:179], v[144:159]
	ds_read_b128 v[234:237], v222 offset:128
	ds_read_b128 v[238:241], v221 offset:128
	v_fmamk_f32 v136, v136, 0x3e0293ee, v208
	v_fmamk_f32 v137, v137, 0x3e0293ee, v208
	v_fmamk_f32 v138, v138, 0x3e0293ee, v208
	v_fmamk_f32 v139, v139, 0x3e0293ee, v208
	v_exp_f32_e32 v136, v136
	v_exp_f32_e32 v137, v137
	v_exp_f32_e32 v138, v138
	v_exp_f32_e32 v139, v139
	v_add_f32_e32 v246, v132, v246
	v_add_f32_e32 v246, v133, v246
	v_add_f32_e32 v246, v134, v246
	v_add_f32_e32 v246, v135, v246
	s_waitcnt lgkmcnt(2)
	v_mfma_f32_32x32x16_bf16 v[144:159], v[226:229], v[172:175], v[144:159]
	v_mfma_f32_32x32x16_bf16 v[144:159], v[230:233], v[168:171], v[144:159]
	v_fmamk_f32 v140, v140, 0x3e0293ee, v208
	v_fmamk_f32 v141, v141, 0x3e0293ee, v208
	v_fmamk_f32 v142, v142, 0x3e0293ee, v208
	v_fmamk_f32 v143, v143, 0x3e0293ee, v208
	v_exp_f32_e32 v140, v140
	v_exp_f32_e32 v141, v141
	v_exp_f32_e32 v142, v142
	v_exp_f32_e32 v143, v143
	v_add_f32_e32 v246, v136, v246
	v_add_f32_e32 v246, v137, v246
	v_add_f32_e32 v246, v138, v246
	v_add_f32_e32 v246, v139, v246
	v_cvt_pk_bf16_f32 v226, v128, v129
	v_cvt_pk_bf16_f32 v227, v130, v131
	v_cvt_pk_bf16_f32 v228, v132, v133
	v_cvt_pk_bf16_f32 v229, v134, v135
	s_waitcnt lgkmcnt(0)
	v_mfma_f32_32x32x16_bf16 v[144:159], v[234:237], v[164:167], v[144:159]
	v_mfma_f32_32x32x16_bf16 v[144:159], v[238:241], v[160:163], v[144:159]
	s_waitcnt vmcnt(0)
	s_barrier
; #define SBAR() __builtin_amdgcn_sched_barrier(0)
; #define PVR(S, DA, DB, vbase) do { S[0] = tr_read<v_rd_off(DA, 0, 0)>(vbase); S[1] = tr_read<v_rd_off(DA, 0, 1)>(vbase); S[2] = tr_read<v_rd_off(DB, 0, 0)>(vbase); S[3] = tr_read<v_rd_off(DB, 0, 1)>(vbase); \
;     S[4] = tr_read<v_rd_off(DA, 1, 0)>(vbase); S[5] = tr_read<v_rd_off(DA, 1, 1)>(vbase); S[6] = tr_read<v_rd_off(DB, 1, 0)>(vbase); S[7] = tr_read<v_rd_off(DB, 1, 1)>(vbase); } while (0)
; #define RAWBAR() do { asm volatile("s_waitcnt lgkmcnt(0)" ::: "memory"); __builtin_amdgcn_s_barrier(); asm volatile("" ::: "memory"); } while (0)
; #define RAWBAR() do { asm volatile("s_waitcnt lgkmcnt(0)" ::: "memory"); __builtin_amdgcn_s_barrier(); asm volatile("" ::: "memory"); } while (0)
; #define RAWBAR() do { asm volatile("s_waitcnt lgkmcnt(0)" ::: "memory"); __builtin_amdgcn_s_barrier(); asm volatile("" ::: "memory"); } while (0)
; #define RAWBAR() do { asm volatile("s_waitcnt lgkmcnt(0)" ::: "memory"); __builtin_amdgcn_s_barrier(); asm volatile("" ::: "memory"); } while (0)
; #define RAWBAR() do { asm volatile("s_waitcnt lgkmcnt(0)" ::: "memory"); __builtin_amdgcn_s_barrier(); asm volatile("" ::: "memory"); } while (0)
; template <int MODE> ...
;     ...
;   for (int j = 0; j < NT; ++j) {
;     const int buf = j & 1;
;     if (j + 1 < NT) { STAGE((j + 1) * KVBLK, buf ^ 1); }
;     const char* Kb = K_lds + buf * 16384;
;     f32x16 pe = {}, po = {};
; #pragma unroll
;     for (int d0 = 0; d0 < 8; d0 += 2) {
;       const bf16x8 k0 = *reinterpret_cast<const bf16x8*>(Kb + KSWZ(krow, (d0 * 16 + hi * 8) * 2));
;       const bf16x8 k1 = *reinterpret_cast<const bf16x8*>(Kb + KSWZ(krow, ((d0 + 1) * 16 + hi * 8) * 2));
;       pe = __builtin_amdgcn_mfma_f32_32x32x16_bf16(k0, qr[d0], pe, 0, 0, 0);
;       po = __builtin_amdgcn_mfma_f32_32x32x16_bf16(k1, qr[d0 + 1], po, 0, 0, 0); }
;     const int vo = vb0 + buf * 32768;
;     s16x4 R0_[8], R1_[8];
;     PVR(R0_, 0, 1, vo);
;     f32x16 p;
; #pragma unroll
;     for (int r = 0; r < 16; ++r) p[r] = __builtin_amdgcn_exp2f(fmaf(pe[r] + po[r], C, negMc));
;     float ps = 0.f;
; #pragma unroll
;     for (int r = 0; r < 16; ++r) ps += p[r];
;     lsum += ps;
;     const bf16x8 own0 = pk8(p, 0), own1 = pk8(p, 8);
;     SBAR();
;     PV_TAIL4(o, vo, vo + 16384, own0, own1);
;     asm volatile("s_waitcnt vmcnt(0)" ::: "memory");
;     RAWBAR();
;   }
	s_add_u32 s86, s86, 0x4000
	s_addc_u32 s87, s87, 0
	s_add_u32 s2, s2, 0x8000
	s_addc_u32 s3, s3, 0
	s_mov_b32 m0, s24
	s_nop 0
	global_load_lds_dwordx4 v220, s[86:87]
	s_add_i32 m0, s24, 0x2000
	s_nop 0
	global_load_lds_dwordx4 v219, s[86:87]
	v_add_u32_e32 v245, s84, v214
	s_sub_u32 s85, s84, 0x8000
	s_cmp_eq_u32 s84, 0
	s_cselect_b32 s85, 0x10000, s85
	ds_read_b64_tr_b16 v[234:235], v245 offset:0
	ds_read_b64_tr_b16 v[236:237], v245 offset:2048
	ds_read_b64_tr_b16 v[238:239], v245 offset:512
	ds_read_b64_tr_b16 v[240:241], v245 offset:2560
	v_permlane32_swap_b32_e32 v226, v228
	v_permlane32_swap_b32_e32 v227, v229
	ds_read_b64_tr_b16 v[128:129], v245 offset:4096
	ds_read_b64_tr_b16 v[130:131], v245 offset:6144
	ds_read_b64_tr_b16 v[132:133], v245 offset:4608
	ds_read_b64_tr_b16 v[134:135], v245 offset:6656
	v_add_f32_e32 v246, v140, v246
	v_add_f32_e32 v246, v141, v246
	v_add_f32_e32 v246, v142, v246
	v_add_f32_e32 v246, v143, v246
	v_cvt_pk_bf16_f32 v230, v136, v137
	v_cvt_pk_bf16_f32 v231, v138, v139
	v_cvt_pk_bf16_f32 v232, v140, v141
	v_cvt_pk_bf16_f32 v233, v142, v143
	v_add_f32_e32 v215, v215, v246
	ds_read_b64_tr_b16 v[136:137], v245 offset:1024
	ds_read_b64_tr_b16 v[138:139], v245 offset:3072
	ds_read_b64_tr_b16 v[140:141], v245 offset:1536
	ds_read_b64_tr_b16 v[142:143], v245 offset:3584
	v_permlane32_swap_b32_e32 v230, v232
	v_permlane32_swap_b32_e32 v231, v233
	s_waitcnt lgkmcnt(8)
	v_mfma_f32_32x32x16_bf16 v[112:127], v[226:229], v[234:237], v[112:127]
	v_mfma_f32_32x32x16_bf16 v[96:111], v[226:229], v[238:241], v[96:111]
	ds_read_b64_tr_b16 v[234:235], v245 offset:5120
	ds_read_b64_tr_b16 v[236:237], v245 offset:7168
	ds_read_b64_tr_b16 v[238:239], v245 offset:5632
	ds_read_b64_tr_b16 v[240:241], v245 offset:7680
	s_add_i32 s41, s85, s24
	s_add_i32 m0, s41, 0x8000
	s_nop 0
	global_load_lds_dwordx4 v218, s[2:3]
	s_waitcnt lgkmcnt(8)
	v_mfma_f32_32x32x16_bf16 v[112:127], v[230:233], v[128:131], v[112:127]
	v_mfma_f32_32x32x16_bf16 v[96:111], v[230:233], v[132:135], v[96:111]
	ds_read_b64_tr_b16 v[128:129], v245 offset:16384
	ds_read_b64_tr_b16 v[130:131], v245 offset:18432
	ds_read_b64_tr_b16 v[132:133], v245 offset:16896
	ds_read_b64_tr_b16 v[134:135], v245 offset:18944
	s_add_i32 s41, s85, s24
	s_add_i32 m0, s41, 0xa000
	s_nop 0
	global_load_lds_dwordx4 v217, s[2:3]
	s_waitcnt lgkmcnt(8)
	v_mfma_f32_32x32x16_bf16 v[80:95], v[226:229], v[136:139], v[80:95]
	v_mfma_f32_32x32x16_bf16 v[64:79], v[226:229], v[140:143], v[64:79]
	ds_read_b64_tr_b16 v[136:137], v245 offset:20480
	ds_read_b64_tr_b16 v[138:139], v245 offset:22528
	ds_read_b64_tr_b16 v[140:141], v245 offset:20992
	ds_read_b64_tr_b16 v[142:143], v245 offset:23040
	s_add_i32 s41, s85, s24
	s_add_i32 m0, s41, 0xc000
	s_nop 0
	global_load_lds_dwordx4 v242, s[2:3]
	s_waitcnt lgkmcnt(8)
	v_mfma_f32_32x32x16_bf16 v[80:95], v[230:233], v[234:237], v[80:95]
	v_mfma_f32_32x32x16_bf16 v[64:79], v[230:233], v[238:241], v[64:79]
	ds_read_b64_tr_b16 v[234:235], v245 offset:17408
	ds_read_b64_tr_b16 v[236:237], v245 offset:19456
	ds_read_b64_tr_b16 v[238:239], v245 offset:17920
	ds_read_b64_tr_b16 v[240:241], v245 offset:19968
	s_add_i32 s41, s85, s24
	s_add_i32 m0, s41, 0xe000
	s_nop 0
	global_load_lds_dwordx4 v243, s[2:3]
	s_waitcnt lgkmcnt(8)
	v_mfma_f32_32x32x16_bf16 v[48:63], v[226:229], v[128:131], v[48:63]
	v_mfma_f32_32x32x16_bf16 v[32:47], v[226:229], v[132:135], v[32:47]
	ds_read_b64_tr_b16 v[128:129], v245 offset:21504
	ds_read_b64_tr_b16 v[130:131], v245 offset:23552
	ds_read_b64_tr_b16 v[132:133], v245 offset:22016
	ds_read_b64_tr_b16 v[134:135], v245 offset:24064
	s_waitcnt lgkmcnt(8)
	v_mfma_f32_32x32x16_bf16 v[48:63], v[230:233], v[136:139], v[48:63]
	v_mfma_f32_32x32x16_bf16 v[32:47], v[230:233], v[140:143], v[32:47]
	s_waitcnt lgkmcnt(0)
	v_mfma_f32_32x32x16_bf16 v[16:31], v[226:229], v[234:237], v[16:31]
	v_mfma_f32_32x32x16_bf16 v[0:15], v[226:229], v[238:241], v[0:15]
	v_mfma_f32_32x32x16_bf16 v[16:31], v[230:233], v[128:131], v[16:31]
	v_mfma_f32_32x32x16_bf16 v[0:15], v[230:233], v[132:135], v[0:15]
	s_add_i32 s84, s84, 0x8000
	s_cmp_eq_u32 s84, 0x18000
	s_cselect_b32 s84, 0, s84
	s_add_i32 s25, s25, 1
	s_cmpk_eq_i32 s25, 0x82
	s_cbranch_scc0 .LattnB_m0
	s_waitcnt vmcnt(0)
	s_barrier

; __device__ __forceinline__ int crow(int r, int hi) { return (r & 3) + 8 * (r >> 2) + 4 * hi; }
; #define XS_WRITE(OV, BASE) do { float* xs_ = (float*)(lds + (BASE)) + ((g * 4) * 64 + lane) * 16; \
;     _Pragma("unroll") for (int d0 = 0; d0 < 4; ++d0) { float* xp = xs_ + d0 * 64 * 16; \
;       _Pragma("unroll") for (int q4 = 0; q4 < 4; ++q4) *(f32x4v*)(xp + 4 * q4) = (f32x4v){OV[d0][4 * q4], OV[d0][4 * q4 + 1], OV[d0][4 * q4 + 2], OV[d0][4 * q4 + 3]}; } } while (0)
; #define XS_WRITE(OV, BASE) do { float* xs_ = (float*)(lds + (BASE)) + ((g * 4) * 64 + lane) * 16; \
;     _Pragma("unroll") for (int d0 = 0; d0 < 4; ++d0) { float* xp = xs_ + d0 * 64 * 16; \
;       _Pragma("unroll") for (int q4 = 0; q4 < 4; ++q4) *(f32x4v*)(xp + 4 * q4) = (f32x4v){OV[d0][4 * q4], OV[d0][4 * q4 + 1], OV[d0][4 * q4 + 2], OV[d0][4 * q4 + 3]}; } } while (0)
; template <int MODE> ...
;     ...
;   L_lds[(wid * 2 + hi) * 32 + r32] = lsum;
;     ...
;   f32x16* olo = o; f32x16* ohi = o + 4;
;   if (kh) { XS_WRITE(olo, 0); } else { XS_WRITE(ohi, 65536); }
;   __syncthreads();
;   if (kh) { XS_ADD(ohi, 65536);
; #pragma unroll
;     for (int d0 = 0; d0 < 4; ++d0) o[d0] = o[4 + d0]; }
;   else { XS_ADD(olo, 0); }
;     ...
;   float rli[16];
; #pragma unroll
;   for (int r = 0; r < 16; ++r) { const int row = crow(r, hi); const float* lp = L_lds + (g * 4) * 32 + row; rli[r] = __builtin_amdgcn_rcpf((lp[0] + lp[32]) + (lp[64] + lp[96])); }
.LBB0_1022:
	s_or_b64 exec, exec, s[24:25]
	v_add3_u32 v80, v129, v128, v130
	ds_read_b128 v[64:67], v80
	ds_read_b128 v[68:71], v80 offset:16
	ds_read_b128 v[72:75], v80 offset:32
	ds_read_b128 v[76:79], v80 offset:48
	s_ashr_i32 s24, s40, 3
	s_ashr_i32 s25, s24, 31
	s_waitcnt lgkmcnt(2)
	v_add_f32_e32 v68, v52, v68
	v_add_f32_e32 v64, v48, v64
	v_add_f32_e32 v65, v49, v65
	v_add_f32_e32 v66, v50, v66
	v_add_f32_e32 v67, v51, v67
	ds_read_b128 v[48:51], v80 offset:4096
	v_add_f32_e32 v69, v53, v69
	v_add_f32_e32 v70, v54, v70
	v_add_f32_e32 v71, v55, v71
	ds_read_b128 v[52:55], v80 offset:4112
	s_waitcnt lgkmcnt(1)
	v_add_f32_e32 v48, v32, v48
	v_add_f32_e32 v49, v33, v49
	v_add_f32_e32 v50, v34, v50
	v_add_f32_e32 v51, v35, v51
	ds_read_b128 v[32:35], v80 offset:4128
	s_waitcnt lgkmcnt(1)
	v_add_f32_e32 v52, v36, v52
	v_add_f32_e32 v53, v37, v53
	v_add_f32_e32 v54, v38, v54
	v_add_f32_e32 v55, v39, v55
	ds_read_b128 v[36:39], v80 offset:4144
	s_waitcnt lgkmcnt(1)
	v_add_f32_e32 v40, v40, v32
	v_add_f32_e32 v41, v41, v33
	v_add_f32_e32 v42, v42, v34
	v_add_f32_e32 v43, v43, v35
	ds_read_b128 v[32:35], v80 offset:8192
	s_waitcnt lgkmcnt(1)
	v_add_f32_e32 v44, v44, v36
	v_add_f32_e32 v45, v45, v37
	v_add_f32_e32 v46, v46, v38
	v_add_f32_e32 v47, v47, v39
	ds_read_b128 v[36:39], v80 offset:8208
	s_waitcnt lgkmcnt(1)
	v_add_f32_e32 v32, v16, v32
	v_add_f32_e32 v33, v17, v33
	v_add_f32_e32 v34, v18, v34
	v_add_f32_e32 v35, v19, v35
	ds_read_b128 v[16:19], v80 offset:8224
	s_waitcnt lgkmcnt(1)
	v_add_f32_e32 v36, v20, v36
	v_add_f32_e32 v37, v21, v37
	v_add_f32_e32 v38, v22, v38
	v_add_f32_e32 v39, v23, v39
	ds_read_b128 v[20:23], v80 offset:8240
	v_add_f32_e32 v56, v56, v72
	v_add_f32_e32 v57, v57, v73
	v_add_f32_e32 v58, v58, v74
	v_add_f32_e32 v59, v59, v75
	s_waitcnt lgkmcnt(1)
	v_add_f32_e32 v72, v24, v16
	v_add_f32_e32 v73, v25, v17
	v_add_f32_e32 v74, v26, v18
	v_add_f32_e32 v75, v27, v19
	ds_read_b128 v[16:19], v80 offset:12288
	v_add_f32_e32 v60, v60, v76
	v_add_f32_e32 v61, v61, v77
	v_add_f32_e32 v62, v62, v78
	v_add_f32_e32 v63, v63, v79
	s_waitcnt lgkmcnt(1)
	v_add_f32_e32 v76, v28, v20
	v_add_f32_e32 v77, v29, v21
	v_add_f32_e32 v78, v30, v22
	v_add_f32_e32 v79, v31, v23
	ds_read_b128 v[20:23], v80 offset:12304
	s_lshl_b32 s2, s40, 8
	s_and_b32 s94, s2, 0x700
	s_lshl_b64 s[2:3], s[24:25], 27
	s_lshl_b64 s[28:29], s[28:29], 20
	s_waitcnt lgkmcnt(1)
	v_add_f32_e32 v81, v0, v16
	v_add_f32_e32 v82, v1, v17
	v_add_f32_e32 v83, v2, v18
	v_add_f32_e32 v84, v3, v19
	ds_read_b128 v[0:3], v80 offset:12320
	s_add_u32 s2, s38, s2
	s_addc_u32 s3, s39, s3
	s_add_u32 s2, s2, s28
	s_waitcnt lgkmcnt(1)
	v_add_f32_e32 v85, v4, v20
	v_add_f32_e32 v86, v5, v21
	v_add_f32_e32 v87, v6, v22
	v_add_f32_e32 v88, v7, v23
	ds_read_b128 v[4:7], v80 offset:12336
	s_addc_u32 s3, s3, s29
	s_lshl_b32 s25, s94, 2
	s_add_u32 s28, s2, s25
	s_waitcnt lgkmcnt(1)
	v_add_f32_e32 v80, v8, v0
	v_and_b32_e32 v0, 0x3fffff80, v197
	s_addc_u32 s29, s3, 0
	v_lshlrev_b32_e32 v0, 2, v0
	s_add_i32 s25, 0, 0x20000
	v_add3_u32 v96, s25, v0, v194
	v_add_f32_e32 v89, v9, v1
	v_add_f32_e32 v90, v10, v2
	v_add_f32_e32 v91, v11, v3
	s_waitcnt lgkmcnt(0)
	v_add_f32_e32 v92, v12, v4
	v_add_f32_e32 v93, v13, v5
	v_add_f32_e32 v94, v14, v6
	v_add_f32_e32 v95, v15, v7
	ds_read_b128 v[0:3], v96 offset:128
	ds_read_b128 v[4:7], v96
	ds_read_b128 v[8:11], v96 offset:32
	ds_read_b128 v[12:15], v96 offset:256
	ds_read_b128 v[16:19], v96 offset:384
	ds_read_b128 v[20:23], v96 offset:160
	s_waitcnt lgkmcnt(4)
	v_add_f32_e32 v0, v4, v0
	ds_read_b128 v[24:27], v96 offset:288
	ds_read_b128 v[28:31], v96 offset:416
	v_ashrrev_i32_e32 v197, 31, v196
	s_waitcnt lgkmcnt(3)
	v_add_f32_e32 v4, v12, v16
	v_add_f32_e32 v0, v0, v4
	v_rcp_f32_e32 v97, v0
	v_add_f32_e32 v0, v5, v1
	v_add_f32_e32 v1, v13, v17
	v_add_f32_e32 v0, v0, v1
	v_rcp_f32_e32 v98, v0
	v_add_f32_e32 v0, v6, v2
	v_add_f32_e32 v1, v14, v18
	v_add_f32_e32 v0, v0, v1
	v_rcp_f32_e32 v99, v0
	v_add_f32_e32 v0, v7, v3
	v_add_f32_e32 v1, v15, v19
	v_add_f32_e32 v0, v0, v1
	v_rcp_f32_e32 v100, v0
	s_waitcnt lgkmcnt(2)
	v_add_f32_e32 v0, v8, v20
	s_waitcnt lgkmcnt(0)
	v_add_f32_e32 v1, v24, v28
	v_add_f32_e32 v0, v0, v1
	v_rcp_f32_e32 v101, v0
	v_add_f32_e32 v0, v9, v21
	v_add_f32_e32 v1, v25, v29
	v_add_f32_e32 v0, v0, v1
	v_rcp_f32_e32 v102, v0
	v_add_f32_e32 v0, v10, v22
	v_add_f32_e32 v1, v26, v30
	v_add_f32_e32 v0, v0, v1
	v_rcp_f32_e32 v103, v0
	v_add_f32_e32 v0, v11, v23
	v_add_f32_e32 v1, v27, v31
	v_add_f32_e32 v0, v0, v1
	v_rcp_f32_e32 v104, v0
	ds_read_b128 v[0:3], v96 offset:64
	ds_read_b128 v[4:7], v96 offset:192
	ds_read_b128 v[8:11], v96 offset:320
	ds_read_b128 v[12:15], v96 offset:448
	ds_read_b128 v[16:19], v96 offset:96
	ds_read_b128 v[20:23], v96 offset:224
	s_waitcnt lgkmcnt(4)
	v_add_f32_e32 v0, v0, v4
	ds_read_b128 v[24:27], v96 offset:352
	ds_read_b128 v[28:31], v96 offset:480
	s_waitcnt lgkmcnt(4)
	v_add_f32_e32 v4, v8, v12
	v_add_f32_e32 v0, v0, v4
	v_rcp_f32_e32 v4, v0
	v_add_f32_e32 v0, v1, v5
	v_add_f32_e32 v1, v9, v13
	v_add_f32_e32 v0, v0, v1
	v_rcp_f32_e32 v5, v0
	v_add_f32_e32 v0, v2, v6
	v_add_f32_e32 v1, v10, v14
	v_add_f32_e32 v0, v0, v1
	v_rcp_f32_e32 v6, v0
	v_add_f32_e32 v0, v3, v7
	v_add_f32_e32 v1, v11, v15
	v_add_f32_e32 v0, v0, v1
	v_rcp_f32_e32 v7, v0
	s_waitcnt lgkmcnt(2)
	v_add_f32_e32 v0, v16, v20
	s_waitcnt lgkmcnt(0)
; __device__ __forceinline__ int crow(int r, int hi) { return (r & 3) + 8 * (r >> 2) + 4 * hi; }
; template <int MODE> ...
;     ...
;   float rli[16];
; #pragma unroll
;   for (int r = 0; r < 16; ++r) { const int row = crow(r, hi); const float* lp = L_lds + (g * 4) * 32 + row; rli[r] = __builtin_amdgcn_rcpf((lp[0] + lp[32]) + (lp[64] + lp[96])); }
;   float* Ow = Ob + (long)(g * 32) * LDO + kh * 128;
;   if (MODE == 0) {
; #pragma unroll
;     for (int r = 0; r < 16; ++r) { const int orow = crow(r, hi);
; #pragma unroll
;       for (int d0 = 0; d0 < 4; ++d0) Ow[(long)orow * LDO + d0 * 32 + r32] = o[d0][r] * rli[r]; }
;     asm volatile("s_waitcnt vmcnt(0)" ::: "memory"); __syncthreads();
	v_add_f32_e32 v1, v24, v28
	v_add_f32_e32 v0, v0, v1
	v_rcp_f32_e32 v8, v0
	v_add_f32_e32 v0, v17, v21
	v_add_f32_e32 v1, v25, v29
	v_add_f32_e32 v0, v0, v1
	v_rcp_f32_e32 v9, v0
	v_add_f32_e32 v0, v18, v22
	v_add_f32_e32 v1, v26, v30
	v_add_f32_e32 v0, v0, v1
	v_rcp_f32_e32 v10, v0
	v_add_f32_e32 v0, v19, v23
	v_add_f32_e32 v1, v27, v31
	v_add_f32_e32 v0, v0, v1
	v_rcp_f32_e32 v11, v0
	v_lshlrev_b64 v[0:1], 13, v[196:197]
	v_lshl_add_u64 v[0:1], s[28:29], 0, v[0:1]
	v_lshlrev_b32_e32 v194, 9, v211
	v_lshl_add_u64 v[0:1], v[0:1], 0, v[194:195]
	v_lshlrev_b32_e32 v194, 2, v206
	v_lshlrev_b32_e32 v2, 15, v207
	v_lshl_add_u64 v[0:1], v[0:1], 0, v[194:195]
	v_mov_b32_e32 v3, v195
	v_lshl_add_u64 v[0:1], v[0:1], 0, v[2:3]
	v_mul_f32_e32 v2, v64, v97
	global_store_dword v[0:1], v2, off
	v_mul_f32_e32 v2, v48, v97
	global_store_dword v[0:1], v2, off offset:128
	v_mul_f32_e32 v2, v32, v97
	global_store_dword v[0:1], v2, off offset:256
	v_mul_f32_e32 v2, v81, v97
	global_store_dword v[0:1], v2, off offset:384
	v_add_co_u32_e32 v2, vcc, s57, v0
	v_mul_f32_e32 v12, v65, v98
	s_nop 0
	v_addc_co_u32_e32 v3, vcc, 0, v1, vcc
	global_store_dword v[2:3], v12, off
	v_mul_f32_e32 v12, v49, v98
	global_store_dword v[2:3], v12, off offset:128
	v_mul_f32_e32 v12, v33, v98
	global_store_dword v[2:3], v12, off offset:256
	v_mul_f32_e32 v12, v82, v98
	global_store_dword v[2:3], v12, off offset:384
	v_add_co_u32_e32 v2, vcc, s62, v0
	v_mul_f32_e32 v12, v66, v99
	s_nop 0
	v_addc_co_u32_e32 v3, vcc, 0, v1, vcc
	global_store_dword v[2:3], v12, off
	v_mul_f32_e32 v12, v50, v99
	global_store_dword v[2:3], v12, off offset:128
	v_mul_f32_e32 v12, v34, v99
	global_store_dword v[2:3], v12, off offset:256
	v_mul_f32_e32 v12, v83, v99
	global_store_dword v[2:3], v12, off offset:384
	v_add_co_u32_e32 v2, vcc, s66, v0
	v_mul_f32_e32 v12, v67, v100
	s_nop 0
	v_addc_co_u32_e32 v3, vcc, 0, v1, vcc
	global_store_dword v[2:3], v12, off
	v_mul_f32_e32 v12, v51, v100
	global_store_dword v[2:3], v12, off offset:128
	v_mul_f32_e32 v12, v35, v100
	global_store_dword v[2:3], v12, off offset:256
	v_mul_f32_e32 v12, v84, v100
	global_store_dword v[2:3], v12, off offset:384
	v_add_co_u32_e32 v2, vcc, s64, v0
	v_mul_f32_e32 v12, v68, v101
	s_nop 0
	v_addc_co_u32_e32 v3, vcc, 0, v1, vcc
	global_store_dword v[2:3], v12, off
	v_mul_f32_e32 v12, v52, v101
	global_store_dword v[2:3], v12, off offset:128
	v_mul_f32_e32 v12, v36, v101
	global_store_dword v[2:3], v12, off offset:256
	v_mul_f32_e32 v12, v85, v101
	global_store_dword v[2:3], v12, off offset:384
	v_add_co_u32_e32 v2, vcc, s67, v0
	v_mul_f32_e32 v12, v69, v102
	s_nop 0
	v_addc_co_u32_e32 v3, vcc, 0, v1, vcc
	global_store_dword v[2:3], v12, off
	v_mul_f32_e32 v12, v53, v102
	global_store_dword v[2:3], v12, off offset:128
	v_mul_f32_e32 v12, v37, v102
	global_store_dword v[2:3], v12, off offset:256
	v_mul_f32_e32 v12, v86, v102
	global_store_dword v[2:3], v12, off offset:384
	v_add_co_u32_e32 v2, vcc, s68, v0
	v_mul_f32_e32 v12, v70, v103
	s_nop 0
	v_addc_co_u32_e32 v3, vcc, 0, v1, vcc
	global_store_dword v[2:3], v12, off
	v_mul_f32_e32 v12, v54, v103
	global_store_dword v[2:3], v12, off offset:128
	v_mul_f32_e32 v12, v38, v103
	global_store_dword v[2:3], v12, off offset:256
	v_mul_f32_e32 v12, v87, v103
	global_store_dword v[2:3], v12, off offset:384
	v_add_co_u32_e32 v2, vcc, s69, v0
	v_mul_f32_e32 v12, v71, v104
	s_nop 0
	v_addc_co_u32_e32 v3, vcc, 0, v1, vcc
	global_store_dword v[2:3], v12, off
	v_mul_f32_e32 v12, v55, v104
	global_store_dword v[2:3], v12, off offset:128
	v_mul_f32_e32 v12, v39, v104
	global_store_dword v[2:3], v12, off offset:256
	v_mul_f32_e32 v12, v88, v104
	global_store_dword v[2:3], v12, off offset:384
	v_add_co_u32_e32 v2, vcc, s63, v0
	v_mul_f32_e32 v12, v56, v4
	s_nop 0
	v_addc_co_u32_e32 v3, vcc, 0, v1, vcc
	global_store_dword v[2:3], v12, off
	v_mul_f32_e32 v12, v40, v4
	global_store_dword v[2:3], v12, off offset:128
	v_mul_f32_e32 v12, v72, v4
	v_mul_f32_e32 v4, v80, v4
	global_store_dword v[2:3], v12, off offset:256
	global_store_dword v[2:3], v4, off offset:384
	v_add_co_u32_e32 v2, vcc, s70, v0
	v_mul_f32_e32 v4, v57, v5
	s_nop 0
	v_addc_co_u32_e32 v3, vcc, 0, v1, vcc
	global_store_dword v[2:3], v4, off
	v_mul_f32_e32 v4, v41, v5
	global_store_dword v[2:3], v4, off offset:128
	v_mul_f32_e32 v4, v73, v5
	global_store_dword v[2:3], v4, off offset:256
	v_mul_f32_e32 v4, v89, v5
	global_store_dword v[2:3], v4, off offset:384
	v_add_co_u32_e32 v2, vcc, s71, v0
	v_mul_f32_e32 v4, v58, v6
	s_nop 0
	v_addc_co_u32_e32 v3, vcc, 0, v1, vcc
	global_store_dword v[2:3], v4, off
	v_mul_f32_e32 v4, v42, v6
	global_store_dword v[2:3], v4, off offset:128
	v_mul_f32_e32 v4, v74, v6
	global_store_dword v[2:3], v4, off offset:256
	v_mul_f32_e32 v4, v90, v6
	global_store_dword v[2:3], v4, off offset:384
	v_add_co_u32_e32 v2, vcc, s72, v0
	v_mul_f32_e32 v4, v59, v7
	s_nop 0
	v_addc_co_u32_e32 v3, vcc, 0, v1, vcc
	global_store_dword v[2:3], v4, off
	v_mul_f32_e32 v4, v43, v7
	global_store_dword v[2:3], v4, off offset:128
	v_mul_f32_e32 v4, v75, v7
	global_store_dword v[2:3], v4, off offset:256
	v_mul_f32_e32 v4, v91, v7
	global_store_dword v[2:3], v4, off offset:384
	v_add_co_u32_e32 v2, vcc, s73, v0
	v_mul_f32_e32 v4, v60, v8
	s_nop 0
	v_addc_co_u32_e32 v3, vcc, 0, v1, vcc
	global_store_dword v[2:3], v4, off
	v_mul_f32_e32 v4, v44, v8
	global_store_dword v[2:3], v4, off offset:128
	v_mul_f32_e32 v4, v76, v8
	global_store_dword v[2:3], v4, off offset:256
	v_mul_f32_e32 v4, v92, v8
	global_store_dword v[2:3], v4, off offset:384
	v_add_co_u32_e32 v2, vcc, s74, v0
	v_mul_f32_e32 v4, v61, v9
	s_nop 0
	v_addc_co_u32_e32 v3, vcc, 0, v1, vcc
	global_store_dword v[2:3], v4, off
	v_mul_f32_e32 v4, v45, v9
	global_store_dword v[2:3], v4, off offset:128
	v_mul_f32_e32 v4, v77, v9
	global_store_dword v[2:3], v4, off offset:256
	v_mul_f32_e32 v4, v93, v9
	global_store_dword v[2:3], v4, off offset:384
	v_add_co_u32_e32 v2, vcc, s75, v0
	v_mul_f32_e32 v4, v62, v10
	s_nop 0
	v_addc_co_u32_e32 v3, vcc, 0, v1, vcc
	global_store_dword v[2:3], v4, off
	v_mul_f32_e32 v4, v46, v10
	global_store_dword v[2:3], v4, off offset:128
	v_mul_f32_e32 v4, v78, v10
	global_store_dword v[2:3], v4, off offset:256
	v_mul_f32_e32 v4, v94, v10
	v_add_co_u32_e32 v0, vcc, s76, v0
	global_store_dword v[2:3], v4, off offset:384
	v_mul_f32_e32 v2, v63, v11
	v_addc_co_u32_e32 v1, vcc, 0, v1, vcc
	global_store_dword v[0:1], v2, off
	v_mul_f32_e32 v2, v47, v11
	global_store_dword v[0:1], v2, off offset:128
	v_mul_f32_e32 v2, v79, v11
	global_store_dword v[0:1], v2, off offset:256
	v_mul_f32_e32 v2, v95, v11
	global_store_dword v[0:1], v2, off offset:384
	v_mov_b32_e32 v194, v224
	s_waitcnt vmcnt(0)
	s_waitcnt vmcnt(63) expcnt(7) lgkmcnt(15)
	s_barrier
; __device__ __forceinline__ int v_rd_base(int lane) { return ((lane & 3) << 3) | (((lane >> 2) & 3) << 6) | (((lane >> 4) & 1) << 5) | (((lane >> 5) & 1) << 8); }
; #define RAWBAR() do { asm volatile("s_waitcnt lgkmcnt(0)" ::: "memory"); __builtin_amdgcn_s_barrier(); asm volatile("" ::: "memory"); } while (0)
; #define RAWBAR() do { asm volatile("s_waitcnt lgkmcnt(0)" ::: "memory"); __builtin_amdgcn_s_barrier(); asm volatile("" ::: "memory"); } while (0)
; #define RAWBAR() do { asm volatile("s_waitcnt lgkmcnt(0)" ::: "memory"); __builtin_amdgcn_s_barrier(); asm volatile("" ::: "memory"); } while (0)
; #define RAWBAR() do { asm volatile("s_waitcnt lgkmcnt(0)" ::: "memory"); __builtin_amdgcn_s_barrier(); asm volatile("" ::: "memory"); } while (0)
; #define RAWBAR() do { asm volatile("s_waitcnt lgkmcnt(0)" ::: "memory"); __builtin_amdgcn_s_barrier(); asm volatile("" ::: "memory"); } while (0)
; #define RAWBAR() do { asm volatile("s_waitcnt lgkmcnt(0)" ::: "memory"); __builtin_amdgcn_s_barrier(); asm volatile("" ::: "memory"); } while (0)
; template <int MODE> ...
;     ...
;   int tid_ = threadIdx.x; asm volatile("" : "+v"(tid_));
;   const int tid = tid_, wid = tid >> 6, lane = tid & 63, r32 = lane & 31, hi = lane >> 5, g = wid >> 1, kh = wid & 1;
;   char* K_lds = lds; char* V_lds = lds + 32768; float* L_lds = (float*)(lds + 131072);
;   constexpr float C = SCALE * 1.4426950408889634f;
;   f32x16 o[8] = {}; bf16x8 qr[8]; float lsum = 0.f;
;   const bf16* Qw = Qb + (long)(g * 32 + r32) * 128 + hi * 8;
; #pragma unroll
;   for (int d0 = 0; d0 < 8; ++d0) qr[d0] = St::ld8(Qw + d0 * 16);
;   const int vb0 = (int)(uintptr_t)V_lds + v_rd_base(lane) + 2 * kh * 4096;
;   const int krow = 32 * kh + r32;
;   typedef __attribute__((address_space(3))) unsigned lds_u32;
;   const int wu = __builtin_amdgcn_readfirstlane(wid);
;   long gk[2], gv[2];
; #pragma unroll
;   for (int c = 0; c < 2; ++c) { const int q = wu + 8 * c;
;     const int r = 4 * q + (lane >> 4), pch = lane & 15; gk[c] = (long)r * 128 + ((pch ^ (r & 7)) * 8);
;     const int st = 2 * q + (lane >> 5), kk = (st >> 2) * 8 + ((lane >> 2) & 7), k = (kk & ~0xC) | ((kk & 4) << 1) | ((kk & 8) >> 1), cc = (st & 3) * 32 + (lane & 3) * 8;
;     gv[c] = (long)k * 256 + cc; }
;     ...
;   const int NT = seq / KVBLK;
;   STAGE(0, 0); asm volatile("s_waitcnt vmcnt(0)" ::: "memory"); RAWBAR();
;   if (false) __builtin_amdgcn_s_setprio(1);
	v_mov_b32_e32 v199, v195
	v_ashrrev_i32_e32 v217, 7, v194
	v_and_b32_e32 v214, 31, v194
	v_lshlrev_b32_e32 v196, 5, v217
	v_or_b32_e32 v0, v196, v214
	v_ashrrev_i32_e32 v1, 31, v0
	v_bfe_u32 v213, v194, 5, 1
	v_lshlrev_b64 v[0:1], 8, v[0:1]
	v_lshl_add_u64 v[0:1], s[34:35], 0, v[0:1]
	v_lshlrev_b32_e32 v198, 4, v213
	v_lshl_add_u64 v[0:1], v[0:1], 0, v[198:199]
	v_lshl_add_u64 v[2:3], v[0:1], 0, s[20:21]
	v_add_co_u32_e32 v0, vcc, s77, v0
	v_ashrrev_i32_e32 v215, 6, v194
	s_add_u32 s36, s36, 0x410000
	v_addc_co_u32_e32 v1, vcc, 0, v1, vcc
	v_readfirstlane_b32 s2, v215
	s_addc_u32 s37, s37, 0
	global_load_dwordx4 v[184:187], v[2:3], off offset:32
	global_load_dwordx4 v[180:183], v[2:3], off offset:64
	global_load_dwordx4 v[176:179], v[2:3], off offset:96
	global_load_dwordx4 v[172:175], v[2:3], off offset:128
	global_load_dwordx4 v[168:171], v[2:3], off offset:160
	global_load_dwordx4 v[164:167], v[2:3], off offset:192
	global_load_dwordx4 v[188:191], v[0:1], off
	global_load_dwordx4 v[160:163], v[2:3], off offset:224
	v_bfe_u32 v199, v194, 4, 2
	v_bfe_u32 v0, v194, 2, 2
	v_lshrrev_b32_e32 v1, 1, v194
	s_lshl_b32 s3, s2, 2
	s_lshl_b32 s34, s2, 1
	v_and_or_b32 v6, v1, 8, v0
	v_or_b32_e32 v0, s3, v199
	s_and_b32 s3, s3, -16
	s_and_b32 s35, s34, 4
	s_or_b32 s3, s3, s35
	v_or_b32_e32 v2, s3, v6
	s_add_i32 s3, s2, 8
	v_and_b32_e32 v4, 63, v194
	v_and_or_b32 v14, s34, 2, v213
	s_lshl_b32 s34, s3, 2
	s_lshl_b32 s35, s3, 1
	v_lshlrev_b32_e32 v8, 3, v4
	v_lshlrev_b32_e32 v197, 4, v4
	v_or_b32_e32 v4, s34, v199
	s_and_b32 s34, s34, -16
	s_and_b32 s41, s35, 4
	v_lshlrev_b32_e32 v9, 1, v194
	v_and_b32_e32 v211, 15, v194
	v_ashrrev_i32_e32 v1, 31, v0
	s_or_b32 s34, s34, s41
	v_and_b32_e32 v12, 0x100, v8
	v_bitop3_b32 v10, v0, v211, 7 bitop3:0x6c
	v_ashrrev_i32_e32 v5, 31, v4
	v_bitop3_b32 v15, v4, v211, 7 bitop3:0x6c
	v_or_b32_e32 v6, s34, v6
	v_and_b32_e32 v17, 24, v8
	v_and_b32_e32 v19, 32, v9
	v_lshlrev_b64 v[8:9], 8, v[0:1]
	s_lshl_b32 s34, s2, 10
	v_lshlrev_b32_e32 v212, 3, v194
	v_and_or_b32 v16, s35, 2, v213
	v_lshl_or_b32 v8, v10, 4, v8
	s_add_i32 s35, s34, 0
	v_lshlrev_b64 v[4:5], 8, v[4:5]
	v_lshlrev_b32_e32 v15, 4, v15
	v_and_b32_e32 v13, 24, v212
	v_ashrrev_i32_e32 v3, 31, v2
	v_lshl_add_u64 v[10:11], s[36:37], 0, v[8:9]
	s_mov_b32 m0, s35
	v_or_b32_e32 v4, v4, v15
	v_ashrrev_i32_e32 v7, 31, v6
	global_load_lds_dwordx4 v[10:11], off
	v_lshl_add_u64 v[128:129], v[10:11], 0, s[18:19]
	v_lshl_add_u64 v[4:5], s[36:37], 0, v[4:5]
	v_lshl_add_u64 v[130:131], v[4:5], 0, s[18:19]
	s_add_i32 m0, s35, 0x2000
	v_lshlrev_b32_e32 v1, 6, v14
	v_lshlrev_b32_e32 v10, 1, v13
	v_lshlrev_b64 v[2:3], 9, v[2:3]
	global_load_lds_dwordx4 v[4:5], off
	s_add_i32 m0, s35, 0x4000
	s_nop 0
	global_load_lds_dwordx4 v[128:129], off
	s_add_i32 m0, s35, 0x6000
	s_nop 0
	global_load_lds_dwordx4 v[130:131], off
	v_or3_b32 v4, v1, v10, v2
	v_mov_b32_e32 v5, v3
	v_lshlrev_b32_e32 v1, 6, v16
	v_lshlrev_b64 v[6:7], 9, v[6:7]
	v_lshl_add_u64 v[4:5], s[30:31], 0, v[4:5]
	s_add_i32 m0, s35, 0x8000
	v_or3_b32 v10, v1, v10, v6
	v_mov_b32_e32 v11, v7
	global_load_lds_dwordx4 v[4:5], off
	v_lshl_add_u64 v[10:11], s[30:31], 0, v[10:11]
	s_add_i32 m0, s35, 0xa000
	v_lshl_add_u64 v[4:5], v[4:5], 0, s[10:11]
	global_load_lds_dwordx4 v[10:11], off
	s_add_i32 m0, s35, 0xc000
	v_and_b32_e32 v216, 1, v215
	global_load_lds_dwordx4 v[4:5], off
	v_lshl_add_u64 v[4:5], v[10:11], 0, s[10:11]
	s_add_i32 m0, s35, 0xe000
	v_lshlrev_b32_e32 v20, 13, v216
	global_load_lds_dwordx4 v[4:5], off
	s_cmp_lg_u32 s33, -1
	v_lshl_or_b32 v1, v214, 8, v20
	s_cselect_b32 s30, s33, 0
	s_and_b32 s2, s2, 1
	v_lshlrev_b32_e32 v4, 4, v194
	v_add_u32_e32 v220, 0, v1
	s_lshl_b32 s2, s2, 6
	v_and_b32_e32 v1, 32, v194
	v_and_b32_e32 v5, 0x70, v4
	v_bitop3_b32 v229, v198, v4, s58 bitop3:0x78
	v_or3_b32 v4, s2, v1, v13
	s_and_b32 s2, s3, 1
	s_lshl_b32 s2, s2, 6
	v_or3_b32 v1, s2, v1, v13
	v_add_u32_e32 v0, 32, v0
	v_and_b32_e32 v18, 0xc0, v197
	s_waitcnt vmcnt(0)
	v_lshl_or_b32 v6, v1, 1, v6
	v_ashrrev_i32_e32 v1, 31, v0
	s_waitcnt lgkmcnt(0)
	s_barrier
	v_add_u32_e32 v10, s30, v18
	v_readlane_b32 s84, v251, 28
	v_lshlrev_b64 v[0:1], 8, v[0:1]
	v_add3_u32 v10, v10, v17, v19
	v_lshl_or_b32 v2, v4, 1, v2
	v_readlane_b32 s85, v251, 29
	v_or_b32_e32 v0, v0, v15
	v_mov_b32_e32 v219, 0
	s_mov_b32 s40, 0
	v_add3_u32 v218, v10, v12, v20
	v_bitop3_b32 v228, v198, v5, 32 bitop3:0x36
	v_bitop3_b32 v227, v198, v5, 64 bitop3:0x36
	v_bitop3_b32 v226, v198, v5, s43 bitop3:0x36
	v_bitop3_b32 v225, v198, v5, s59 bitop3:0x36
	v_bitop3_b32 v223, v198, v5, s60 bitop3:0x36
	v_bitop3_b32 v222, v198, v5, s56 bitop3:0x36
	v_bitop3_b32 v221, v198, v5, s61 bitop3:0x36
	v_lshl_add_u64 v[200:201], s[84:85], 0, v[2:3]
	v_lshl_add_u64 v[202:203], s[84:85], 0, v[6:7]
	v_lshl_add_u64 v[204:205], s[8:9], 0, v[8:9]
	v_lshl_add_u64 v[206:207], s[8:9], 0, v[0:1]
	v_mov_b32_e32 v0, 0
	v_mov_b32_e32 v1, v219
	v_mov_b32_e32 v2, v219
	v_mov_b32_e32 v3, v219
	v_mov_b32_e32 v4, v219
	v_mov_b32_e32 v5, v219
	v_mov_b32_e32 v6, v219
	v_mov_b32_e32 v7, v219
	v_mov_b32_e32 v8, v219
	v_mov_b32_e32 v9, v219
	v_mov_b32_e32 v10, v219
	v_mov_b32_e32 v11, v219
	v_mov_b32_e32 v12, v219
	v_mov_b32_e32 v13, v219
	v_mov_b32_e32 v14, v219
	v_mov_b32_e32 v15, v219
	v_mov_b32_e32 v48, 0
	v_mov_b32_e32 v49, v219
	v_mov_b32_e32 v50, v219
	v_mov_b32_e32 v51, v219
	v_mov_b32_e32 v52, v219
	v_mov_b32_e32 v53, v219
	v_mov_b32_e32 v54, v219
	v_mov_b32_e32 v55, v219
	v_mov_b32_e32 v56, v219
	v_mov_b32_e32 v57, v219
	v_mov_b32_e32 v58, v219
	v_mov_b32_e32 v59, v219
	v_mov_b32_e32 v60, v219
	v_mov_b32_e32 v61, v219
	v_mov_b32_e32 v62, v219
	v_mov_b32_e32 v63, v219
	v_mov_b32_e32 v16, 0
; __device__ __forceinline__ int v_rd_base(int lane) { return ((lane & 3) << 3) | (((lane >> 2) & 3) << 6) | (((lane >> 4) & 1) << 5) | (((lane >> 5) & 1) << 8); }
; #define RAWBAR() do { asm volatile("s_waitcnt lgkmcnt(0)" ::: "memory"); __builtin_amdgcn_s_barrier(); asm volatile("" ::: "memory"); } while (0)
; #define RAWBAR() do { asm volatile("s_waitcnt lgkmcnt(0)" ::: "memory"); __builtin_amdgcn_s_barrier(); asm volatile("" ::: "memory"); } while (0)
; template <int MODE> ...
;     ...
;   f32x16 o[8] = {}; bf16x8 qr[8]; float lsum = 0.f;
;   const bf16* Qw = Qb + (long)(g * 32 + r32) * 128 + hi * 8;
; #pragma unroll
;   for (int d0 = 0; d0 < 8; ++d0) qr[d0] = St::ld8(Qw + d0 * 16);
;   const int vb0 = (int)(uintptr_t)V_lds + v_rd_base(lane) + 2 * kh * 4096;
;   const int krow = 32 * kh + r32;
;   typedef __attribute__((address_space(3))) unsigned lds_u32;
;   const int wu = __builtin_amdgcn_readfirstlane(wid);
;   long gk[2], gv[2];
; #pragma unroll
;   for (int c = 0; c < 2; ++c) { const int q = wu + 8 * c;
;     const int r = 4 * q + (lane >> 4), pch = lane & 15; gk[c] = (long)r * 128 + ((pch ^ (r & 7)) * 8);
;     const int st = 2 * q + (lane >> 5), kk = (st >> 2) * 8 + ((lane >> 2) & 7), k = (kk & ~0xC) | ((kk & 4) << 1) | ((kk & 8) >> 1), cc = (st & 3) * 32 + (lane & 3) * 8;
;     gv[c] = (long)k * 256 + cc; }
;     ...
;   const int NT = seq / KVBLK;
;   STAGE(0, 0); asm volatile("s_waitcnt vmcnt(0)" ::: "memory"); RAWBAR();
;   if (false) __builtin_amdgcn_s_setprio(1);
;   for (int j = 0; j < NT; ++j) {
;     const int buf = j & 1;
;     if (j + 1 < NT) { STAGE((j + 1) * KVBLK, buf ^ 1); }
;     const char* Kb = K_lds + buf * 16384;
;     f32x16 pe = {}, po = {};
; #pragma unroll
;     for (int d0 = 0; d0 < 8; d0 += 2) {
;       const bf16x8 k0 = *reinterpret_cast<const bf16x8*>(Kb + KSWZ(krow, (d0 * 16 + hi * 8) * 2));
;       const bf16x8 k1 = *reinterpret_cast<const bf16x8*>(Kb + KSWZ(krow, ((d0 + 1) * 16 + hi * 8) * 2));
;       pe = __builtin_amdgcn_mfma_f32_32x32x16_bf16(k0, qr[d0], pe, 0, 0, 0);
;       po = __builtin_amdgcn_mfma_f32_32x32x16_bf16(k1, qr[d0 + 1], po, 0, 0, 0); }
;     const int vo = vb0 + buf * 32768;
;     s16x4 R0_[8], R1_[8];
;     PVR(R0_, 0, 1, vo);
;     f32x16 p;
; #pragma unroll
;     for (int r = 0; r < 16; ++r) p[r] = __builtin_amdgcn_exp2f(fmaf(pe[r] + po[r], C, negMc));
	v_mov_b32_e32 v17, v219
	v_mov_b32_e32 v18, v219
	v_mov_b32_e32 v19, v219
	v_mov_b32_e32 v20, v219
	v_mov_b32_e32 v21, v219
	v_mov_b32_e32 v22, v219
	v_mov_b32_e32 v23, v219
	v_mov_b32_e32 v24, v219
	v_mov_b32_e32 v25, v219
	v_mov_b32_e32 v26, v219
	v_mov_b32_e32 v27, v219
	v_mov_b32_e32 v28, v219
	v_mov_b32_e32 v29, v219
	v_mov_b32_e32 v30, v219
	v_mov_b32_e32 v31, v219
	v_mov_b32_e32 v32, 0
	v_mov_b32_e32 v33, v219
	v_mov_b32_e32 v34, v219
	v_mov_b32_e32 v35, v219
	v_mov_b32_e32 v36, v219
	v_mov_b32_e32 v37, v219
	v_mov_b32_e32 v38, v219
	v_mov_b32_e32 v39, v219
	v_mov_b32_e32 v40, v219
	v_mov_b32_e32 v41, v219
	v_mov_b32_e32 v42, v219
	v_mov_b32_e32 v43, v219
	v_mov_b32_e32 v44, v219
	v_mov_b32_e32 v45, v219
	v_mov_b32_e32 v46, v219
	v_mov_b32_e32 v47, v219
	v_mov_b32_e32 v64, 0
	v_mov_b32_e32 v65, v219
	v_mov_b32_e32 v66, v219
	v_mov_b32_e32 v67, v219
	v_mov_b32_e32 v68, v219
	v_mov_b32_e32 v69, v219
	v_mov_b32_e32 v70, v219
	v_mov_b32_e32 v71, v219
	v_mov_b32_e32 v72, v219
	v_mov_b32_e32 v73, v219
	v_mov_b32_e32 v74, v219
	v_mov_b32_e32 v75, v219
	v_mov_b32_e32 v76, v219
	v_mov_b32_e32 v77, v219
	v_mov_b32_e32 v78, v219
	v_mov_b32_e32 v79, v219
	v_mov_b32_e32 v80, 0
	v_mov_b32_e32 v81, v219
	v_mov_b32_e32 v82, v219
	v_mov_b32_e32 v83, v219
	v_mov_b32_e32 v84, v219
	v_mov_b32_e32 v85, v219
	v_mov_b32_e32 v86, v219
	v_mov_b32_e32 v87, v219
	v_mov_b32_e32 v88, v219
	v_mov_b32_e32 v89, v219
	v_mov_b32_e32 v90, v219
	v_mov_b32_e32 v91, v219
	v_mov_b32_e32 v92, v219
	v_mov_b32_e32 v93, v219
	v_mov_b32_e32 v94, v219
	v_mov_b32_e32 v95, v219
	v_mov_b32_e32 v96, 0
	v_mov_b32_e32 v97, v219
	v_mov_b32_e32 v98, v219
	v_mov_b32_e32 v99, v219
	v_mov_b32_e32 v100, v219
	v_mov_b32_e32 v101, v219
	v_mov_b32_e32 v102, v219
	v_mov_b32_e32 v103, v219
	v_mov_b32_e32 v104, v219
	v_mov_b32_e32 v105, v219
	v_mov_b32_e32 v106, v219
	v_mov_b32_e32 v107, v219
	v_mov_b32_e32 v108, v219
	v_mov_b32_e32 v109, v219
	v_mov_b32_e32 v110, v219
	v_mov_b32_e32 v111, v219
	v_mov_b32_e32 v112, 0
	v_mov_b32_e32 v113, v219
	v_mov_b32_e32 v114, v219
	v_mov_b32_e32 v115, v219
	v_mov_b32_e32 v116, v219
	v_mov_b32_e32 v117, v219
	v_mov_b32_e32 v118, v219
	v_mov_b32_e32 v119, v219
	v_mov_b32_e32 v120, v219
	v_mov_b32_e32 v121, v219
	v_mov_b32_e32 v122, v219
	v_mov_b32_e32 v123, v219
	v_mov_b32_e32 v124, v219
	v_mov_b32_e32 v125, v219
	v_mov_b32_e32 v126, v219
	v_mov_b32_e32 v127, v219
	v_readlane_b32 s86, v251, 30
	v_readlane_b32 s87, v251, 31
	s_waitcnt vmcnt(0)
	v_subrev_u32_e32 v225, s8, v204
	v_subrev_u32_e32 v223, s8, v206
	v_subrev_u32_e32 v222, s84, v200
	v_subrev_u32_e32 v221, s84, v202
	v_add_u32_e32 v246, 0x100, v222
	v_add_u32_e32 v247, 0x100, v221
	s_add_u32 s86, s8, s26
	s_addc_u32 s87, s9, s27
	s_add_u32 s86, s86, 0x4000
	s_addc_u32 s87, s87, 0
	s_add_u32 s2, s84, s26
	s_addc_u32 s3, s85, s27
	s_add_u32 s2, s2, s12
	s_addc_u32 s3, s3, s13
	v_add_u32_e32 v229, v220, v229
	v_add_u32_e32 v228, v220, v228
	v_add_u32_e32 v227, v220, v227
	v_add_u32_e32 v226, v220, v226
	ds_read_b128 v[230:233], v229 offset:0
	ds_read_b128 v[234:237], v228 offset:0
	s_waitcnt lgkmcnt(0)
	v_mfma_f32_32x32x16_bf16 v[144:159], v[230:233], v[188:191], 0
	v_mfma_f32_32x32x16_bf16 v[144:159], v[234:237], v[184:187], v[144:159]
	ds_read_b128 v[230:233], v227 offset:0
	ds_read_b128 v[234:237], v226 offset:0
	s_waitcnt lgkmcnt(0)
	v_mfma_f32_32x32x16_bf16 v[144:159], v[230:233], v[180:183], v[144:159]
	v_mfma_f32_32x32x16_bf16 v[144:159], v[234:237], v[176:179], v[144:159]
	ds_read_b128 v[230:233], v229 offset:128
	ds_read_b128 v[234:237], v228 offset:128
	s_waitcnt lgkmcnt(0)
	v_mfma_f32_32x32x16_bf16 v[144:159], v[230:233], v[172:175], v[144:159]
	v_mfma_f32_32x32x16_bf16 v[144:159], v[234:237], v[168:171], v[144:159]
	ds_read_b128 v[230:233], v227 offset:128
	ds_read_b128 v[234:237], v226 offset:128
	s_waitcnt lgkmcnt(0)
	v_mfma_f32_32x32x16_bf16 v[144:159], v[230:233], v[164:167], v[144:159]
	v_mfma_f32_32x32x16_bf16 v[144:159], v[234:237], v[160:163], v[144:159]
	s_mov_b32 s84, 0
	s_barrier
	s_cmp_lt_u32 s34, 0x1000
	s_cbranch_scc0 .LattnBpre_m1
.LBB0_1023:
	ds_read_b128 v[230:233], v229 offset:16384
	ds_read_b128 v[234:237], v228 offset:16384
	ds_read_b128 v[238:241], v227 offset:16384
	ds_read_b128 v[242:245], v226 offset:16384
	s_mov_b32 m0, s34
	s_nop 0
	global_load_lds_dwordx4 v225, s[86:87]
	s_add_i32 m0, s34, 0x2000
	s_nop 0
	global_load_lds_dwordx4 v223, s[86:87]
	v_fmamk_f32 v144, v144, 0x3e0293ee, v208
	v_fmamk_f32 v145, v145, 0x3e0293ee, v208
	v_fmamk_f32 v146, v146, 0x3e0293ee, v208
	v_fmamk_f32 v147, v147, 0x3e0293ee, v208
	v_exp_f32_e32 v144, v144
	v_exp_f32_e32 v145, v145
	v_exp_f32_e32 v146, v146
	v_exp_f32_e32 v147, v147
	s_waitcnt lgkmcnt(2)
	v_mfma_f32_32x32x16_bf16 v[128:143], v[230:233], v[188:191], 0
	v_mfma_f32_32x32x16_bf16 v[128:143], v[234:237], v[184:187], v[128:143]
	ds_read_b128 v[230:233], v229 offset:16512
	ds_read_b128 v[234:237], v228 offset:16512
	v_fmamk_f32 v148, v148, 0x3e0293ee, v208
	v_fmamk_f32 v149, v149, 0x3e0293ee, v208
	v_fmamk_f32 v150, v150, 0x3e0293ee, v208
	v_fmamk_f32 v151, v151, 0x3e0293ee, v208
	v_exp_f32_e32 v148, v148
	v_exp_f32_e32 v149, v149
	v_exp_f32_e32 v150, v150
	v_exp_f32_e32 v151, v151
	v_add_f32_e32 v250, v144, v145
	v_add_f32_e32 v250, v146, v250
	v_add_f32_e32 v250, v147, v250
	s_waitcnt lgkmcnt(2)
	v_mfma_f32_32x32x16_bf16 v[128:143], v[238:241], v[180:183], v[128:143]
	v_mfma_f32_32x32x16_bf16 v[128:143], v[242:245], v[176:179], v[128:143]
	ds_read_b128 v[238:241], v227 offset:16512
	ds_read_b128 v[242:245], v226 offset:16512
	v_fmamk_f32 v152, v152, 0x3e0293ee, v208
	v_fmamk_f32 v153, v153, 0x3e0293ee, v208
	v_fmamk_f32 v154, v154, 0x3e0293ee, v208
	v_fmamk_f32 v155, v155, 0x3e0293ee, v208
	v_exp_f32_e32 v152, v152
	v_exp_f32_e32 v153, v153
	v_exp_f32_e32 v154, v154
	v_exp_f32_e32 v155, v155
	v_add_f32_e32 v250, v148, v250
	v_add_f32_e32 v250, v149, v250
	v_add_f32_e32 v250, v150, v250
	v_add_f32_e32 v250, v151, v250
	s_waitcnt lgkmcnt(2)
; #define SBAR() __builtin_amdgcn_sched_barrier(0)
; #define PVR(S, DA, DB, vbase) do { S[0] = tr_read<v_rd_off(DA, 0, 0)>(vbase); S[1] = tr_read<v_rd_off(DA, 0, 1)>(vbase); S[2] = tr_read<v_rd_off(DB, 0, 0)>(vbase); S[3] = tr_read<v_rd_off(DB, 0, 1)>(vbase); \
;     S[4] = tr_read<v_rd_off(DA, 1, 0)>(vbase); S[5] = tr_read<v_rd_off(DA, 1, 1)>(vbase); S[6] = tr_read<v_rd_off(DB, 1, 0)>(vbase); S[7] = tr_read<v_rd_off(DB, 1, 1)>(vbase); } while (0)
; #define RAWBAR() do { asm volatile("s_waitcnt lgkmcnt(0)" ::: "memory"); __builtin_amdgcn_s_barrier(); asm volatile("" ::: "memory"); } while (0)
; #define RAWBAR() do { asm volatile("s_waitcnt lgkmcnt(0)" ::: "memory"); __builtin_amdgcn_s_barrier(); asm volatile("" ::: "memory"); } while (0)
; #define RAWBAR() do { asm volatile("s_waitcnt lgkmcnt(0)" ::: "memory"); __builtin_amdgcn_s_barrier(); asm volatile("" ::: "memory"); } while (0)
; #define RAWBAR() do { asm volatile("s_waitcnt lgkmcnt(0)" ::: "memory"); __builtin_amdgcn_s_barrier(); asm volatile("" ::: "memory"); } while (0)
; #define RAWBAR() do { asm volatile("s_waitcnt lgkmcnt(0)" ::: "memory"); __builtin_amdgcn_s_barrier(); asm volatile("" ::: "memory"); } while (0)
; template <int MODE> ...
;     ...
;   for (int j = 0; j < NT; ++j) {
;     const int buf = j & 1;
;     if (j + 1 < NT) { STAGE((j + 1) * KVBLK, buf ^ 1); }
;     const char* Kb = K_lds + buf * 16384;
;     f32x16 pe = {}, po = {};
; #pragma unroll
;     for (int d0 = 0; d0 < 8; d0 += 2) {
;       const bf16x8 k0 = *reinterpret_cast<const bf16x8*>(Kb + KSWZ(krow, (d0 * 16 + hi * 8) * 2));
;       const bf16x8 k1 = *reinterpret_cast<const bf16x8*>(Kb + KSWZ(krow, ((d0 + 1) * 16 + hi * 8) * 2));
;       pe = __builtin_amdgcn_mfma_f32_32x32x16_bf16(k0, qr[d0], pe, 0, 0, 0);
;       po = __builtin_amdgcn_mfma_f32_32x32x16_bf16(k1, qr[d0 + 1], po, 0, 0, 0); }
;     const int vo = vb0 + buf * 32768;
;     s16x4 R0_[8], R1_[8];
;     PVR(R0_, 0, 1, vo);
;     f32x16 p;
; #pragma unroll
;     for (int r = 0; r < 16; ++r) p[r] = __builtin_amdgcn_exp2f(fmaf(pe[r] + po[r], C, negMc));
;     float ps = 0.f;
; #pragma unroll
;     for (int r = 0; r < 16; ++r) ps += p[r];
;     lsum += ps;
;     const bf16x8 own0 = pk8(p, 0), own1 = pk8(p, 8);
;     SBAR();
;     PV_TAIL4(o, vo, vo + 16384, own0, own1);
;     asm volatile("s_waitcnt vmcnt(0)" ::: "memory");
;     RAWBAR();
;   }
	v_mfma_f32_32x32x16_bf16 v[128:143], v[230:233], v[172:175], v[128:143]
	v_mfma_f32_32x32x16_bf16 v[128:143], v[234:237], v[168:171], v[128:143]
	v_fmamk_f32 v156, v156, 0x3e0293ee, v208
	v_fmamk_f32 v157, v157, 0x3e0293ee, v208
	v_fmamk_f32 v158, v158, 0x3e0293ee, v208
	v_fmamk_f32 v159, v159, 0x3e0293ee, v208
	v_exp_f32_e32 v156, v156
	v_exp_f32_e32 v157, v157
	v_exp_f32_e32 v158, v158
	v_exp_f32_e32 v159, v159
	v_add_f32_e32 v250, v152, v250
	v_add_f32_e32 v250, v153, v250
	v_add_f32_e32 v250, v154, v250
	v_add_f32_e32 v250, v155, v250
	v_cvt_pk_bf16_f32 v230, v144, v145
	v_cvt_pk_bf16_f32 v231, v146, v147
	v_cvt_pk_bf16_f32 v232, v148, v149
	v_cvt_pk_bf16_f32 v233, v150, v151
	s_waitcnt lgkmcnt(0)
	v_mfma_f32_32x32x16_bf16 v[128:143], v[238:241], v[164:167], v[128:143]
	v_mfma_f32_32x32x16_bf16 v[128:143], v[242:245], v[160:163], v[128:143]
	v_add_u32_e32 v249, s84, v218
	s_add_i32 s85, s84, 0x8000
	s_cmp_eq_u32 s85, 0x18000
	s_cselect_b32 s85, 0, s85
	ds_read_b64_tr_b16 v[238:239], v249 offset:0
	ds_read_b64_tr_b16 v[240:241], v249 offset:2048
	ds_read_b64_tr_b16 v[242:243], v249 offset:512
	ds_read_b64_tr_b16 v[244:245], v249 offset:2560
	v_permlane32_swap_b32_e32 v230, v232
	v_permlane32_swap_b32_e32 v231, v233
	ds_read_b64_tr_b16 v[144:145], v249 offset:4096
	ds_read_b64_tr_b16 v[146:147], v249 offset:6144
	ds_read_b64_tr_b16 v[148:149], v249 offset:4608
	ds_read_b64_tr_b16 v[150:151], v249 offset:6656
	v_add_f32_e32 v250, v156, v250
	v_add_f32_e32 v250, v157, v250
	v_add_f32_e32 v250, v158, v250
	v_add_f32_e32 v250, v159, v250
	v_cvt_pk_bf16_f32 v234, v152, v153
	v_cvt_pk_bf16_f32 v235, v154, v155
	v_cvt_pk_bf16_f32 v236, v156, v157
	v_cvt_pk_bf16_f32 v237, v158, v159
	v_add_f32_e32 v219, v219, v250
	ds_read_b64_tr_b16 v[152:153], v249 offset:1024
	ds_read_b64_tr_b16 v[154:155], v249 offset:3072
	ds_read_b64_tr_b16 v[156:157], v249 offset:1536
	ds_read_b64_tr_b16 v[158:159], v249 offset:3584
	v_permlane32_swap_b32_e32 v234, v236
	v_permlane32_swap_b32_e32 v235, v237
	s_waitcnt lgkmcnt(8)
	v_mfma_f32_32x32x16_bf16 v[112:127], v[230:233], v[238:241], v[112:127]
	v_mfma_f32_32x32x16_bf16 v[96:111], v[230:233], v[242:245], v[96:111]
	ds_read_b64_tr_b16 v[238:239], v249 offset:5120
	ds_read_b64_tr_b16 v[240:241], v249 offset:7168
	ds_read_b64_tr_b16 v[242:243], v249 offset:5632
	ds_read_b64_tr_b16 v[244:245], v249 offset:7680
	s_add_i32 s30, s85, s34
	s_add_i32 m0, s30, 0x8000
	s_nop 0
	global_load_lds_dwordx4 v222, s[2:3]
	s_waitcnt lgkmcnt(8)
	v_mfma_f32_32x32x16_bf16 v[112:127], v[234:237], v[144:147], v[112:127]
	v_mfma_f32_32x32x16_bf16 v[96:111], v[234:237], v[148:151], v[96:111]
	ds_read_b64_tr_b16 v[144:145], v249 offset:16384
	ds_read_b64_tr_b16 v[146:147], v249 offset:18432
	ds_read_b64_tr_b16 v[148:149], v249 offset:16896
	ds_read_b64_tr_b16 v[150:151], v249 offset:18944
	s_add_i32 s30, s85, s34
	s_add_i32 m0, s30, 0xa000
	s_nop 0
	global_load_lds_dwordx4 v221, s[2:3]
	s_waitcnt lgkmcnt(8)
	v_mfma_f32_32x32x16_bf16 v[80:95], v[230:233], v[152:155], v[80:95]
	v_mfma_f32_32x32x16_bf16 v[64:79], v[230:233], v[156:159], v[64:79]
	ds_read_b64_tr_b16 v[152:153], v249 offset:20480
	ds_read_b64_tr_b16 v[154:155], v249 offset:22528
	ds_read_b64_tr_b16 v[156:157], v249 offset:20992
	ds_read_b64_tr_b16 v[158:159], v249 offset:23040
	s_add_i32 s30, s85, s34
	s_add_i32 m0, s30, 0xc000
	s_nop 0
	global_load_lds_dwordx4 v246, s[2:3]
	s_waitcnt lgkmcnt(8)
	v_mfma_f32_32x32x16_bf16 v[80:95], v[234:237], v[238:241], v[80:95]
	v_mfma_f32_32x32x16_bf16 v[64:79], v[234:237], v[242:245], v[64:79]
	ds_read_b64_tr_b16 v[238:239], v249 offset:17408
	ds_read_b64_tr_b16 v[240:241], v249 offset:19456
	ds_read_b64_tr_b16 v[242:243], v249 offset:17920
	ds_read_b64_tr_b16 v[244:245], v249 offset:19968
	s_add_i32 s30, s85, s34
	s_add_i32 m0, s30, 0xe000
	s_nop 0
	global_load_lds_dwordx4 v247, s[2:3]
	s_waitcnt lgkmcnt(8)
	v_mfma_f32_32x32x16_bf16 v[32:47], v[230:233], v[144:147], v[32:47]
	v_mfma_f32_32x32x16_bf16 v[16:31], v[230:233], v[148:151], v[16:31]
	ds_read_b64_tr_b16 v[144:145], v249 offset:21504
	ds_read_b64_tr_b16 v[146:147], v249 offset:23552
	ds_read_b64_tr_b16 v[148:149], v249 offset:22016
	ds_read_b64_tr_b16 v[150:151], v249 offset:24064
	s_waitcnt lgkmcnt(8)
	v_mfma_f32_32x32x16_bf16 v[32:47], v[234:237], v[152:155], v[32:47]
	v_mfma_f32_32x32x16_bf16 v[16:31], v[234:237], v[156:159], v[16:31]
	s_waitcnt lgkmcnt(0)
	v_mfma_f32_32x32x16_bf16 v[48:63], v[230:233], v[238:241], v[48:63]
	s_waitcnt vmcnt(0)
	s_barrier
; #define SBAR() __builtin_amdgcn_sched_barrier(0)
; #define PVR(S, DA, DB, vbase) do { S[0] = tr_read<v_rd_off(DA, 0, 0)>(vbase); S[1] = tr_read<v_rd_off(DA, 0, 1)>(vbase); S[2] = tr_read<v_rd_off(DB, 0, 0)>(vbase); S[3] = tr_read<v_rd_off(DB, 0, 1)>(vbase); \
;     S[4] = tr_read<v_rd_off(DA, 1, 0)>(vbase); S[5] = tr_read<v_rd_off(DA, 1, 1)>(vbase); S[6] = tr_read<v_rd_off(DB, 1, 0)>(vbase); S[7] = tr_read<v_rd_off(DB, 1, 1)>(vbase); } while (0)
; #define RAWBAR() do { asm volatile("s_waitcnt lgkmcnt(0)" ::: "memory"); __builtin_amdgcn_s_barrier(); asm volatile("" ::: "memory"); } while (0)
; #define RAWBAR() do { asm volatile("s_waitcnt lgkmcnt(0)" ::: "memory"); __builtin_amdgcn_s_barrier(); asm volatile("" ::: "memory"); } while (0)
; #define RAWBAR() do { asm volatile("s_waitcnt lgkmcnt(0)" ::: "memory"); __builtin_amdgcn_s_barrier(); asm volatile("" ::: "memory"); } while (0)
; #define RAWBAR() do { asm volatile("s_waitcnt lgkmcnt(0)" ::: "memory"); __builtin_amdgcn_s_barrier(); asm volatile("" ::: "memory"); } while (0)
; #define RAWBAR() do { asm volatile("s_waitcnt lgkmcnt(0)" ::: "memory"); __builtin_amdgcn_s_barrier(); asm volatile("" ::: "memory"); } while (0)
; template <int MODE> ...
;     ...
;   for (int j = 0; j < NT; ++j) {
;     const int buf = j & 1;
;     if (j + 1 < NT) { STAGE((j + 1) * KVBLK, buf ^ 1); }
;     const char* Kb = K_lds + buf * 16384;
;     f32x16 pe = {}, po = {};
; #pragma unroll
;     for (int d0 = 0; d0 < 8; d0 += 2) {
;       const bf16x8 k0 = *reinterpret_cast<const bf16x8*>(Kb + KSWZ(krow, (d0 * 16 + hi * 8) * 2));
;       const bf16x8 k1 = *reinterpret_cast<const bf16x8*>(Kb + KSWZ(krow, ((d0 + 1) * 16 + hi * 8) * 2));
;       pe = __builtin_amdgcn_mfma_f32_32x32x16_bf16(k0, qr[d0], pe, 0, 0, 0);
;       po = __builtin_amdgcn_mfma_f32_32x32x16_bf16(k1, qr[d0 + 1], po, 0, 0, 0); }
;     const int vo = vb0 + buf * 32768;
;     s16x4 R0_[8], R1_[8];
;     PVR(R0_, 0, 1, vo);
;     f32x16 p;
; #pragma unroll
;     for (int r = 0; r < 16; ++r) p[r] = __builtin_amdgcn_exp2f(fmaf(pe[r] + po[r], C, negMc));
;     float ps = 0.f;
; #pragma unroll
;     for (int r = 0; r < 16; ++r) ps += p[r];
;     lsum += ps;
;     const bf16x8 own0 = pk8(p, 0), own1 = pk8(p, 8);
;     SBAR();
;     PV_TAIL4(o, vo, vo + 16384, own0, own1);
;     asm volatile("s_waitcnt vmcnt(0)" ::: "memory");
;     RAWBAR();
;   }
	s_add_u32 s86, s86, 0x4000
	s_addc_u32 s87, s87, 0
	s_add_u32 s2, s2, 0x8000
	s_addc_u32 s3, s3, 0
	v_mfma_f32_32x32x16_bf16 v[0:15], v[230:233], v[242:245], v[0:15]
	v_mfma_f32_32x32x16_bf16 v[48:63], v[234:237], v[144:147], v[48:63]
	v_mfma_f32_32x32x16_bf16 v[0:15], v[234:237], v[148:151], v[0:15]
	s_add_i32 s84, s84, 0x8000
	s_cmp_eq_u32 s84, 0x18000
	s_cselect_b32 s84, 0, s84
	ds_read_b128 v[230:233], v229 offset:0
	ds_read_b128 v[234:237], v228 offset:0
	ds_read_b128 v[238:241], v227 offset:0
	ds_read_b128 v[242:245], v226 offset:0
	s_add_i32 m0, s34, 0x4000
	s_nop 0
	global_load_lds_dwordx4 v225, s[86:87]
	s_add_i32 m0, s34, 0x6000
	s_nop 0
	global_load_lds_dwordx4 v223, s[86:87]
	v_fmamk_f32 v128, v128, 0x3e0293ee, v208
	v_fmamk_f32 v129, v129, 0x3e0293ee, v208
	v_fmamk_f32 v130, v130, 0x3e0293ee, v208
	v_fmamk_f32 v131, v131, 0x3e0293ee, v208
	v_exp_f32_e32 v128, v128
	v_exp_f32_e32 v129, v129
	v_exp_f32_e32 v130, v130
	v_exp_f32_e32 v131, v131
	s_waitcnt lgkmcnt(2)
	v_mfma_f32_32x32x16_bf16 v[144:159], v[230:233], v[188:191], 0
	v_mfma_f32_32x32x16_bf16 v[144:159], v[234:237], v[184:187], v[144:159]
	ds_read_b128 v[230:233], v229 offset:128
	ds_read_b128 v[234:237], v228 offset:128
	v_fmamk_f32 v132, v132, 0x3e0293ee, v208
	v_fmamk_f32 v133, v133, 0x3e0293ee, v208
	v_fmamk_f32 v134, v134, 0x3e0293ee, v208
	v_fmamk_f32 v135, v135, 0x3e0293ee, v208
	v_exp_f32_e32 v132, v132
	v_exp_f32_e32 v133, v133
	v_exp_f32_e32 v134, v134
	v_exp_f32_e32 v135, v135
	v_add_f32_e32 v250, v128, v129
	v_add_f32_e32 v250, v130, v250
	v_add_f32_e32 v250, v131, v250
	s_waitcnt lgkmcnt(2)
	v_mfma_f32_32x32x16_bf16 v[144:159], v[238:241], v[180:183], v[144:159]
	v_mfma_f32_32x32x16_bf16 v[144:159], v[242:245], v[176:179], v[144:159]
	ds_read_b128 v[238:241], v227 offset:128
	ds_read_b128 v[242:245], v226 offset:128
	v_fmamk_f32 v136, v136, 0x3e0293ee, v208
	v_fmamk_f32 v137, v137, 0x3e0293ee, v208
	v_fmamk_f32 v138, v138, 0x3e0293ee, v208
	v_fmamk_f32 v139, v139, 0x3e0293ee, v208
	v_exp_f32_e32 v136, v136
	v_exp_f32_e32 v137, v137
	v_exp_f32_e32 v138, v138
	v_exp_f32_e32 v139, v139
	v_add_f32_e32 v250, v132, v250
	v_add_f32_e32 v250, v133, v250
	v_add_f32_e32 v250, v134, v250
	v_add_f32_e32 v250, v135, v250
	s_waitcnt lgkmcnt(2)
	v_mfma_f32_32x32x16_bf16 v[144:159], v[230:233], v[172:175], v[144:159]
	v_mfma_f32_32x32x16_bf16 v[144:159], v[234:237], v[168:171], v[144:159]
	v_fmamk_f32 v140, v140, 0x3e0293ee, v208
	v_fmamk_f32 v141, v141, 0x3e0293ee, v208
	v_fmamk_f32 v142, v142, 0x3e0293ee, v208
	v_fmamk_f32 v143, v143, 0x3e0293ee, v208
	v_exp_f32_e32 v140, v140
	v_exp_f32_e32 v141, v141
	v_exp_f32_e32 v142, v142
	v_exp_f32_e32 v143, v143
	v_add_f32_e32 v250, v136, v250
	v_add_f32_e32 v250, v137, v250
	v_add_f32_e32 v250, v138, v250
	v_add_f32_e32 v250, v139, v250
	v_cvt_pk_bf16_f32 v230, v128, v129
	v_cvt_pk_bf16_f32 v231, v130, v131
	v_cvt_pk_bf16_f32 v232, v132, v133
	v_cvt_pk_bf16_f32 v233, v134, v135
	s_waitcnt lgkmcnt(0)
	v_mfma_f32_32x32x16_bf16 v[144:159], v[238:241], v[164:167], v[144:159]
	v_mfma_f32_32x32x16_bf16 v[144:159], v[242:245], v[160:163], v[144:159]
	v_add_u32_e32 v249, s84, v218
	s_add_i32 s85, s84, 0x8000
	s_cmp_eq_u32 s85, 0x18000
	s_cselect_b32 s85, 0, s85
	ds_read_b64_tr_b16 v[238:239], v249 offset:0
	ds_read_b64_tr_b16 v[240:241], v249 offset:2048
	ds_read_b64_tr_b16 v[242:243], v249 offset:512
	ds_read_b64_tr_b16 v[244:245], v249 offset:2560
	v_permlane32_swap_b32_e32 v230, v232
	v_permlane32_swap_b32_e32 v231, v233
	ds_read_b64_tr_b16 v[128:129], v249 offset:4096
	ds_read_b64_tr_b16 v[130:131], v249 offset:6144
	ds_read_b64_tr_b16 v[132:133], v249 offset:4608
	ds_read_b64_tr_b16 v[134:135], v249 offset:6656
	v_add_f32_e32 v250, v140, v250
	v_add_f32_e32 v250, v141, v250
	v_add_f32_e32 v250, v142, v250
	v_add_f32_e32 v250, v143, v250
	v_cvt_pk_bf16_f32 v234, v136, v137
	v_cvt_pk_bf16_f32 v235, v138, v139
	v_cvt_pk_bf16_f32 v236, v140, v141
	v_cvt_pk_bf16_f32 v237, v142, v143
	v_add_f32_e32 v219, v219, v250
	ds_read_b64_tr_b16 v[136:137], v249 offset:1024
	ds_read_b64_tr_b16 v[138:139], v249 offset:3072
	ds_read_b64_tr_b16 v[140:141], v249 offset:1536
	ds_read_b64_tr_b16 v[142:143], v249 offset:3584
	v_permlane32_swap_b32_e32 v234, v236
	v_permlane32_swap_b32_e32 v235, v237
	s_waitcnt lgkmcnt(8)
	v_mfma_f32_32x32x16_bf16 v[112:127], v[230:233], v[238:241], v[112:127]
	v_mfma_f32_32x32x16_bf16 v[96:111], v[230:233], v[242:245], v[96:111]
	ds_read_b64_tr_b16 v[238:239], v249 offset:5120
	ds_read_b64_tr_b16 v[240:241], v249 offset:7168
	ds_read_b64_tr_b16 v[242:243], v249 offset:5632
	ds_read_b64_tr_b16 v[244:245], v249 offset:7680
	s_add_i32 s30, s85, s34
	s_add_i32 m0, s30, 0x8000
	s_nop 0
	global_load_lds_dwordx4 v222, s[2:3]
	s_waitcnt lgkmcnt(8)
	v_mfma_f32_32x32x16_bf16 v[112:127], v[234:237], v[128:131], v[112:127]
	v_mfma_f32_32x32x16_bf16 v[96:111], v[234:237], v[132:135], v[96:111]
	ds_read_b64_tr_b16 v[128:129], v249 offset:16384
	ds_read_b64_tr_b16 v[130:131], v249 offset:18432
	ds_read_b64_tr_b16 v[132:133], v249 offset:16896
	ds_read_b64_tr_b16 v[134:135], v249 offset:18944
	s_add_i32 s30, s85, s34
	s_add_i32 m0, s30, 0xa000
	s_nop 0
	global_load_lds_dwordx4 v221, s[2:3]
	s_waitcnt lgkmcnt(8)
	v_mfma_f32_32x32x16_bf16 v[80:95], v[230:233], v[136:139], v[80:95]
	v_mfma_f32_32x32x16_bf16 v[64:79], v[230:233], v[140:143], v[64:79]
	ds_read_b64_tr_b16 v[136:137], v249 offset:20480
	ds_read_b64_tr_b16 v[138:139], v249 offset:22528
	ds_read_b64_tr_b16 v[140:141], v249 offset:20992
	ds_read_b64_tr_b16 v[142:143], v249 offset:23040
	s_add_i32 s30, s85, s34
	s_add_i32 m0, s30, 0xc000
	s_nop 0
	global_load_lds_dwordx4 v246, s[2:3]
	s_waitcnt lgkmcnt(8)
	v_mfma_f32_32x32x16_bf16 v[80:95], v[234:237], v[238:241], v[80:95]
	v_mfma_f32_32x32x16_bf16 v[64:79], v[234:237], v[242:245], v[64:79]
	ds_read_b64_tr_b16 v[238:239], v249 offset:17408
	ds_read_b64_tr_b16 v[240:241], v249 offset:19456
	ds_read_b64_tr_b16 v[242:243], v249 offset:17920
	ds_read_b64_tr_b16 v[244:245], v249 offset:19968
	s_add_i32 s30, s85, s34
	s_add_i32 m0, s30, 0xe000
	s_nop 0
	global_load_lds_dwordx4 v247, s[2:3]
	s_waitcnt lgkmcnt(8)
	v_mfma_f32_32x32x16_bf16 v[32:47], v[230:233], v[128:131], v[32:47]
	v_mfma_f32_32x32x16_bf16 v[16:31], v[230:233], v[132:135], v[16:31]
	ds_read_b64_tr_b16 v[128:129], v249 offset:21504
	ds_read_b64_tr_b16 v[130:131], v249 offset:23552
	ds_read_b64_tr_b16 v[132:133], v249 offset:22016
	ds_read_b64_tr_b16 v[134:135], v249 offset:24064
	s_waitcnt lgkmcnt(8)
	v_mfma_f32_32x32x16_bf16 v[32:47], v[234:237], v[136:139], v[32:47]
	v_mfma_f32_32x32x16_bf16 v[16:31], v[234:237], v[140:143], v[16:31]
	s_waitcnt lgkmcnt(0)
	v_mfma_f32_32x32x16_bf16 v[48:63], v[230:233], v[238:241], v[48:63]
	s_waitcnt vmcnt(0)
	s_barrier
; #define SBAR() __builtin_amdgcn_sched_barrier(0)
; #define PVR(S, DA, DB, vbase) do { S[0] = tr_read<v_rd_off(DA, 0, 0)>(vbase); S[1] = tr_read<v_rd_off(DA, 0, 1)>(vbase); S[2] = tr_read<v_rd_off(DB, 0, 0)>(vbase); S[3] = tr_read<v_rd_off(DB, 0, 1)>(vbase); \
;     S[4] = tr_read<v_rd_off(DA, 1, 0)>(vbase); S[5] = tr_read<v_rd_off(DA, 1, 1)>(vbase); S[6] = tr_read<v_rd_off(DB, 1, 0)>(vbase); S[7] = tr_read<v_rd_off(DB, 1, 1)>(vbase); } while (0)
; #define RAWBAR() do { asm volatile("s_waitcnt lgkmcnt(0)" ::: "memory"); __builtin_amdgcn_s_barrier(); asm volatile("" ::: "memory"); } while (0)
; #define RAWBAR() do { asm volatile("s_waitcnt lgkmcnt(0)" ::: "memory"); __builtin_amdgcn_s_barrier(); asm volatile("" ::: "memory"); } while (0)
; #define RAWBAR() do { asm volatile("s_waitcnt lgkmcnt(0)" ::: "memory"); __builtin_amdgcn_s_barrier(); asm volatile("" ::: "memory"); } while (0)
; #define RAWBAR() do { asm volatile("s_waitcnt lgkmcnt(0)" ::: "memory"); __builtin_amdgcn_s_barrier(); asm volatile("" ::: "memory"); } while (0)
; #define RAWBAR() do { asm volatile("s_waitcnt lgkmcnt(0)" ::: "memory"); __builtin_amdgcn_s_barrier(); asm volatile("" ::: "memory"); } while (0)
; template <int MODE> ...
;     ...
;   for (int j = 0; j < NT; ++j) {
;     const int buf = j & 1;
;     if (j + 1 < NT) { STAGE((j + 1) * KVBLK, buf ^ 1); }
;     const char* Kb = K_lds + buf * 16384;
;     f32x16 pe = {}, po = {};
; #pragma unroll
;     for (int d0 = 0; d0 < 8; d0 += 2) {
;       const bf16x8 k0 = *reinterpret_cast<const bf16x8*>(Kb + KSWZ(krow, (d0 * 16 + hi * 8) * 2));
;       const bf16x8 k1 = *reinterpret_cast<const bf16x8*>(Kb + KSWZ(krow, ((d0 + 1) * 16 + hi * 8) * 2));
;       pe = __builtin_amdgcn_mfma_f32_32x32x16_bf16(k0, qr[d0], pe, 0, 0, 0);
;       po = __builtin_amdgcn_mfma_f32_32x32x16_bf16(k1, qr[d0 + 1], po, 0, 0, 0); }
;     const int vo = vb0 + buf * 32768;
;     s16x4 R0_[8], R1_[8];
;     PVR(R0_, 0, 1, vo);
;     f32x16 p;
; #pragma unroll
;     for (int r = 0; r < 16; ++r) p[r] = __builtin_amdgcn_exp2f(fmaf(pe[r] + po[r], C, negMc));
;     float ps = 0.f;
; #pragma unroll
;     for (int r = 0; r < 16; ++r) ps += p[r];
;     lsum += ps;
;     const bf16x8 own0 = pk8(p, 0), own1 = pk8(p, 8);
;     SBAR();
;     PV_TAIL4(o, vo, vo + 16384, own0, own1);
;     asm volatile("s_waitcnt vmcnt(0)" ::: "memory");
;     RAWBAR();
;   }
	s_add_u32 s86, s86, 0x4000
	s_addc_u32 s87, s87, 0
	s_add_u32 s2, s2, 0x8000
	s_addc_u32 s3, s3, 0
	v_mfma_f32_32x32x16_bf16 v[0:15], v[230:233], v[242:245], v[0:15]
	v_mfma_f32_32x32x16_bf16 v[48:63], v[234:237], v[128:131], v[48:63]
	v_mfma_f32_32x32x16_bf16 v[0:15], v[234:237], v[132:135], v[0:15]
	s_add_i32 s84, s84, 0x8000
	s_cmp_eq_u32 s84, 0x18000
	s_cselect_b32 s84, 0, s84
	s_add_i32 s40, s40, 1
	s_cmpk_eq_i32 s40, 0x82
	s_cbranch_scc0 .LBB0_1023
	s_barrier
	s_branch .Lattn_join_m1
.LattnBpre_m1:
	s_mov_b32 m0, s34
	s_nop 0
	global_load_lds_dwordx4 v225, s[86:87]
	s_add_i32 m0, s34, 0x2000
	s_nop 0
	global_load_lds_dwordx4 v223, s[86:87]
	s_add_i32 s85, s84, 0x8000
	s_cmp_eq_u32 s85, 0x18000
	s_cselect_b32 s85, 0, s85
	s_add_i32 s30, s85, s34
	s_add_i32 m0, s30, 0x8000
	s_nop 0
	global_load_lds_dwordx4 v222, s[2:3]
	s_add_i32 s30, s85, s34
	s_add_i32 m0, s30, 0xa000
	s_nop 0
	global_load_lds_dwordx4 v221, s[2:3]
	s_add_i32 s30, s85, s34
	s_add_i32 m0, s30, 0xc000
	s_nop 0
	global_load_lds_dwordx4 v246, s[2:3]
	s_add_i32 s30, s85, s34
	s_add_i32 m0, s30, 0xe000
	s_nop 0
	global_load_lds_dwordx4 v247, s[2:3]
.LattnB_m1:
	ds_read_b128 v[230:233], v229 offset:16384
	ds_read_b128 v[234:237], v228 offset:16384
	ds_read_b128 v[238:241], v227 offset:16384
	ds_read_b128 v[242:245], v226 offset:16384
	v_fmamk_f32 v144, v144, 0x3e0293ee, v208
	v_fmamk_f32 v145, v145, 0x3e0293ee, v208
	v_fmamk_f32 v146, v146, 0x3e0293ee, v208
	v_fmamk_f32 v147, v147, 0x3e0293ee, v208
	v_exp_f32_e32 v144, v144
	v_exp_f32_e32 v145, v145
	v_exp_f32_e32 v146, v146
	v_exp_f32_e32 v147, v147
	s_waitcnt lgkmcnt(2)
	v_mfma_f32_32x32x16_bf16 v[128:143], v[230:233], v[188:191], 0
	v_mfma_f32_32x32x16_bf16 v[128:143], v[234:237], v[184:187], v[128:143]
	ds_read_b128 v[230:233], v229 offset:16512
	ds_read_b128 v[234:237], v228 offset:16512
	v_fmamk_f32 v148, v148, 0x3e0293ee, v208
	v_fmamk_f32 v149, v149, 0x3e0293ee, v208
	v_fmamk_f32 v150, v150, 0x3e0293ee, v208
	v_fmamk_f32 v151, v151, 0x3e0293ee, v208
	v_exp_f32_e32 v148, v148
	v_exp_f32_e32 v149, v149
	v_exp_f32_e32 v150, v150
	v_exp_f32_e32 v151, v151
	v_add_f32_e32 v250, v144, v145
	v_add_f32_e32 v250, v146, v250
	v_add_f32_e32 v250, v147, v250
	s_waitcnt lgkmcnt(2)
	v_mfma_f32_32x32x16_bf16 v[128:143], v[238:241], v[180:183], v[128:143]
	v_mfma_f32_32x32x16_bf16 v[128:143], v[242:245], v[176:179], v[128:143]
	ds_read_b128 v[238:241], v227 offset:16512
	ds_read_b128 v[242:245], v226 offset:16512
	v_fmamk_f32 v152, v152, 0x3e0293ee, v208
	v_fmamk_f32 v153, v153, 0x3e0293ee, v208
	v_fmamk_f32 v154, v154, 0x3e0293ee, v208
	v_fmamk_f32 v155, v155, 0x3e0293ee, v208
	v_exp_f32_e32 v152, v152
	v_exp_f32_e32 v153, v153
	v_exp_f32_e32 v154, v154
	v_exp_f32_e32 v155, v155
	v_add_f32_e32 v250, v148, v250
	v_add_f32_e32 v250, v149, v250
	v_add_f32_e32 v250, v150, v250
	v_add_f32_e32 v250, v151, v250
	s_waitcnt lgkmcnt(2)
	v_mfma_f32_32x32x16_bf16 v[128:143], v[230:233], v[172:175], v[128:143]
	v_mfma_f32_32x32x16_bf16 v[128:143], v[234:237], v[168:171], v[128:143]
	v_fmamk_f32 v156, v156, 0x3e0293ee, v208
	v_fmamk_f32 v157, v157, 0x3e0293ee, v208
	v_fmamk_f32 v158, v158, 0x3e0293ee, v208
	v_fmamk_f32 v159, v159, 0x3e0293ee, v208
	v_exp_f32_e32 v156, v156
	v_exp_f32_e32 v157, v157
	v_exp_f32_e32 v158, v158
	v_exp_f32_e32 v159, v159
	v_add_f32_e32 v250, v152, v250
	v_add_f32_e32 v250, v153, v250
	v_add_f32_e32 v250, v154, v250
	v_add_f32_e32 v250, v155, v250
	v_cvt_pk_bf16_f32 v230, v144, v145
	v_cvt_pk_bf16_f32 v231, v146, v147
	v_cvt_pk_bf16_f32 v232, v148, v149
	v_cvt_pk_bf16_f32 v233, v150, v151
	s_waitcnt lgkmcnt(0)
	v_mfma_f32_32x32x16_bf16 v[128:143], v[238:241], v[164:167], v[128:143]
	v_mfma_f32_32x32x16_bf16 v[128:143], v[242:245], v[160:163], v[128:143]
	s_waitcnt vmcnt(0)
	s_barrier
	s_add_u32 s86, s86, 0x4000
	s_addc_u32 s87, s87, 0
	s_add_u32 s2, s2, 0x8000
	s_addc_u32 s3, s3, 0
	s_add_i32 m0, s34, 0x4000
	s_nop 0
	global_load_lds_dwordx4 v225, s[86:87]
	s_add_i32 m0, s34, 0x6000
	s_nop 0
	global_load_lds_dwordx4 v223, s[86:87]
	v_add_u32_e32 v249, s84, v218
	s_sub_u32 s85, s84, 0x8000
	s_cmp_eq_u32 s84, 0
	s_cselect_b32 s85, 0x10000, s85
	ds_read_b64_tr_b16 v[238:239], v249 offset:0
	ds_read_b64_tr_b16 v[240:241], v249 offset:2048
	ds_read_b64_tr_b16 v[242:243], v249 offset:512
	ds_read_b64_tr_b16 v[244:245], v249 offset:2560
	v_permlane32_swap_b32_e32 v230, v232
	v_permlane32_swap_b32_e32 v231, v233
	ds_read_b64_tr_b16 v[144:145], v249 offset:4096
	ds_read_b64_tr_b16 v[146:147], v249 offset:6144
	ds_read_b64_tr_b16 v[148:149], v249 offset:4608
	ds_read_b64_tr_b16 v[150:151], v249 offset:6656
	v_add_f32_e32 v250, v156, v250
	v_add_f32_e32 v250, v157, v250
	v_add_f32_e32 v250, v158, v250
	v_add_f32_e32 v250, v159, v250
	v_cvt_pk_bf16_f32 v234, v152, v153
	v_cvt_pk_bf16_f32 v235, v154, v155
	v_cvt_pk_bf16_f32 v236, v156, v157
	v_cvt_pk_bf16_f32 v237, v158, v159
	v_add_f32_e32 v219, v219, v250
	ds_read_b64_tr_b16 v[152:153], v249 offset:1024
	ds_read_b64_tr_b16 v[154:155], v249 offset:3072
	ds_read_b64_tr_b16 v[156:157], v249 offset:1536
	ds_read_b64_tr_b16 v[158:159], v249 offset:3584
	v_permlane32_swap_b32_e32 v234, v236
	v_permlane32_swap_b32_e32 v235, v237
	s_waitcnt lgkmcnt(8)
	v_mfma_f32_32x32x16_bf16 v[112:127], v[230:233], v[238:241], v[112:127]
	v_mfma_f32_32x32x16_bf16 v[96:111], v[230:233], v[242:245], v[96:111]
	ds_read_b64_tr_b16 v[238:239], v249 offset:5120
	ds_read_b64_tr_b16 v[240:241], v249 offset:7168
	ds_read_b64_tr_b16 v[242:243], v249 offset:5632
	ds_read_b64_tr_b16 v[244:245], v249 offset:7680
	s_add_i32 s30, s85, s34
	s_add_i32 m0, s30, 0x8000
	s_nop 0
	global_load_lds_dwordx4 v222, s[2:3]
	s_waitcnt lgkmcnt(8)
; #define SBAR() __builtin_amdgcn_sched_barrier(0)
; #define PVR(S, DA, DB, vbase) do { S[0] = tr_read<v_rd_off(DA, 0, 0)>(vbase); S[1] = tr_read<v_rd_off(DA, 0, 1)>(vbase); S[2] = tr_read<v_rd_off(DB, 0, 0)>(vbase); S[3] = tr_read<v_rd_off(DB, 0, 1)>(vbase); \
;     S[4] = tr_read<v_rd_off(DA, 1, 0)>(vbase); S[5] = tr_read<v_rd_off(DA, 1, 1)>(vbase); S[6] = tr_read<v_rd_off(DB, 1, 0)>(vbase); S[7] = tr_read<v_rd_off(DB, 1, 1)>(vbase); } while (0)
; #define RAWBAR() do { asm volatile("s_waitcnt lgkmcnt(0)" ::: "memory"); __builtin_amdgcn_s_barrier(); asm volatile("" ::: "memory"); } while (0)
; #define RAWBAR() do { asm volatile("s_waitcnt lgkmcnt(0)" ::: "memory"); __builtin_amdgcn_s_barrier(); asm volatile("" ::: "memory"); } while (0)
; #define RAWBAR() do { asm volatile("s_waitcnt lgkmcnt(0)" ::: "memory"); __builtin_amdgcn_s_barrier(); asm volatile("" ::: "memory"); } while (0)
; #define RAWBAR() do { asm volatile("s_waitcnt lgkmcnt(0)" ::: "memory"); __builtin_amdgcn_s_barrier(); asm volatile("" ::: "memory"); } while (0)
; #define RAWBAR() do { asm volatile("s_waitcnt lgkmcnt(0)" ::: "memory"); __builtin_amdgcn_s_barrier(); asm volatile("" ::: "memory"); } while (0)
; template <int MODE> ...
;     ...
;   for (int j = 0; j < NT; ++j) {
;     const int buf = j & 1;
;     if (j + 1 < NT) { STAGE((j + 1) * KVBLK, buf ^ 1); }
;     const char* Kb = K_lds + buf * 16384;
;     f32x16 pe = {}, po = {};
; #pragma unroll
;     for (int d0 = 0; d0 < 8; d0 += 2) {
;       const bf16x8 k0 = *reinterpret_cast<const bf16x8*>(Kb + KSWZ(krow, (d0 * 16 + hi * 8) * 2));
;       const bf16x8 k1 = *reinterpret_cast<const bf16x8*>(Kb + KSWZ(krow, ((d0 + 1) * 16 + hi * 8) * 2));
;       pe = __builtin_amdgcn_mfma_f32_32x32x16_bf16(k0, qr[d0], pe, 0, 0, 0);
;       po = __builtin_amdgcn_mfma_f32_32x32x16_bf16(k1, qr[d0 + 1], po, 0, 0, 0); }
;     const int vo = vb0 + buf * 32768;
;     s16x4 R0_[8], R1_[8];
;     PVR(R0_, 0, 1, vo);
;     f32x16 p;
; #pragma unroll
;     for (int r = 0; r < 16; ++r) p[r] = __builtin_amdgcn_exp2f(fmaf(pe[r] + po[r], C, negMc));
;     float ps = 0.f;
; #pragma unroll
;     for (int r = 0; r < 16; ++r) ps += p[r];
;     lsum += ps;
;     const bf16x8 own0 = pk8(p, 0), own1 = pk8(p, 8);
;     SBAR();
;     PV_TAIL4(o, vo, vo + 16384, own0, own1);
;     asm volatile("s_waitcnt vmcnt(0)" ::: "memory");
;     RAWBAR();
;   }
	v_mfma_f32_32x32x16_bf16 v[112:127], v[234:237], v[144:147], v[112:127]
	v_mfma_f32_32x32x16_bf16 v[96:111], v[234:237], v[148:151], v[96:111]
	ds_read_b64_tr_b16 v[144:145], v249 offset:16384
	ds_read_b64_tr_b16 v[146:147], v249 offset:18432
	ds_read_b64_tr_b16 v[148:149], v249 offset:16896
	ds_read_b64_tr_b16 v[150:151], v249 offset:18944
	s_add_i32 s30, s85, s34
	s_add_i32 m0, s30, 0xa000
	s_nop 0
	global_load_lds_dwordx4 v221, s[2:3]
	s_waitcnt lgkmcnt(8)
	v_mfma_f32_32x32x16_bf16 v[80:95], v[230:233], v[152:155], v[80:95]
	v_mfma_f32_32x32x16_bf16 v[64:79], v[230:233], v[156:159], v[64:79]
	ds_read_b64_tr_b16 v[152:153], v249 offset:20480
	ds_read_b64_tr_b16 v[154:155], v249 offset:22528
	ds_read_b64_tr_b16 v[156:157], v249 offset:20992
	ds_read_b64_tr_b16 v[158:159], v249 offset:23040
	s_add_i32 s30, s85, s34
	s_add_i32 m0, s30, 0xc000
	s_nop 0
	global_load_lds_dwordx4 v246, s[2:3]
	s_waitcnt lgkmcnt(8)
	v_mfma_f32_32x32x16_bf16 v[80:95], v[234:237], v[238:241], v[80:95]
	v_mfma_f32_32x32x16_bf16 v[64:79], v[234:237], v[242:245], v[64:79]
	ds_read_b64_tr_b16 v[238:239], v249 offset:17408
	ds_read_b64_tr_b16 v[240:241], v249 offset:19456
	ds_read_b64_tr_b16 v[242:243], v249 offset:17920
	ds_read_b64_tr_b16 v[244:245], v249 offset:19968
	s_add_i32 s30, s85, s34
	s_add_i32 m0, s30, 0xe000
	s_nop 0
	global_load_lds_dwordx4 v247, s[2:3]
	s_waitcnt lgkmcnt(8)
	v_mfma_f32_32x32x16_bf16 v[32:47], v[230:233], v[144:147], v[32:47]
	v_mfma_f32_32x32x16_bf16 v[16:31], v[230:233], v[148:151], v[16:31]
	ds_read_b64_tr_b16 v[144:145], v249 offset:21504
	ds_read_b64_tr_b16 v[146:147], v249 offset:23552
	ds_read_b64_tr_b16 v[148:149], v249 offset:22016
	ds_read_b64_tr_b16 v[150:151], v249 offset:24064
	s_waitcnt lgkmcnt(8)
	v_mfma_f32_32x32x16_bf16 v[32:47], v[234:237], v[152:155], v[32:47]
	v_mfma_f32_32x32x16_bf16 v[16:31], v[234:237], v[156:159], v[16:31]
	s_waitcnt lgkmcnt(0)
	v_mfma_f32_32x32x16_bf16 v[48:63], v[230:233], v[238:241], v[48:63]
	v_mfma_f32_32x32x16_bf16 v[0:15], v[230:233], v[242:245], v[0:15]
	v_mfma_f32_32x32x16_bf16 v[48:63], v[234:237], v[144:147], v[48:63]
	v_mfma_f32_32x32x16_bf16 v[0:15], v[234:237], v[148:151], v[0:15]
	s_add_i32 s84, s84, 0x8000
	s_cmp_eq_u32 s84, 0x18000
	s_cselect_b32 s84, 0, s84
	ds_read_b128 v[230:233], v229 offset:0
	ds_read_b128 v[234:237], v228 offset:0
	ds_read_b128 v[238:241], v227 offset:0
	ds_read_b128 v[242:245], v226 offset:0
	v_fmamk_f32 v128, v128, 0x3e0293ee, v208
	v_fmamk_f32 v129, v129, 0x3e0293ee, v208
	v_fmamk_f32 v130, v130, 0x3e0293ee, v208
	v_fmamk_f32 v131, v131, 0x3e0293ee, v208
	v_exp_f32_e32 v128, v128
	v_exp_f32_e32 v129, v129
	v_exp_f32_e32 v130, v130
	v_exp_f32_e32 v131, v131
	s_waitcnt lgkmcnt(2)
	v_mfma_f32_32x32x16_bf16 v[144:159], v[230:233], v[188:191], 0
	v_mfma_f32_32x32x16_bf16 v[144:159], v[234:237], v[184:187], v[144:159]
	ds_read_b128 v[230:233], v229 offset:128
	ds_read_b128 v[234:237], v228 offset:128
	v_fmamk_f32 v132, v132, 0x3e0293ee, v208
	v_fmamk_f32 v133, v133, 0x3e0293ee, v208
	v_fmamk_f32 v134, v134, 0x3e0293ee, v208
	v_fmamk_f32 v135, v135, 0x3e0293ee, v208
	v_exp_f32_e32 v132, v132
	v_exp_f32_e32 v133, v133
	v_exp_f32_e32 v134, v134
	v_exp_f32_e32 v135, v135
	v_add_f32_e32 v250, v128, v129
	v_add_f32_e32 v250, v130, v250
	v_add_f32_e32 v250, v131, v250
	s_waitcnt lgkmcnt(2)
	v_mfma_f32_32x32x16_bf16 v[144:159], v[238:241], v[180:183], v[144:159]
	v_mfma_f32_32x32x16_bf16 v[144:159], v[242:245], v[176:179], v[144:159]
	ds_read_b128 v[238:241], v227 offset:128
	ds_read_b128 v[242:245], v226 offset:128
	v_fmamk_f32 v136, v136, 0x3e0293ee, v208
	v_fmamk_f32 v137, v137, 0x3e0293ee, v208
	v_fmamk_f32 v138, v138, 0x3e0293ee, v208
	v_fmamk_f32 v139, v139, 0x3e0293ee, v208
	v_exp_f32_e32 v136, v136
	v_exp_f32_e32 v137, v137
	v_exp_f32_e32 v138, v138
	v_exp_f32_e32 v139, v139
	v_add_f32_e32 v250, v132, v250
	v_add_f32_e32 v250, v133, v250
	v_add_f32_e32 v250, v134, v250
	v_add_f32_e32 v250, v135, v250
	s_waitcnt lgkmcnt(2)
	v_mfma_f32_32x32x16_bf16 v[144:159], v[230:233], v[172:175], v[144:159]
	v_mfma_f32_32x32x16_bf16 v[144:159], v[234:237], v[168:171], v[144:159]
	v_fmamk_f32 v140, v140, 0x3e0293ee, v208
	v_fmamk_f32 v141, v141, 0x3e0293ee, v208
	v_fmamk_f32 v142, v142, 0x3e0293ee, v208
	v_fmamk_f32 v143, v143, 0x3e0293ee, v208
	v_exp_f32_e32 v140, v140
	v_exp_f32_e32 v141, v141
	v_exp_f32_e32 v142, v142
	v_exp_f32_e32 v143, v143
	v_add_f32_e32 v250, v136, v250
	v_add_f32_e32 v250, v137, v250
	v_add_f32_e32 v250, v138, v250
	v_add_f32_e32 v250, v139, v250
	v_cvt_pk_bf16_f32 v230, v128, v129
	v_cvt_pk_bf16_f32 v231, v130, v131
	v_cvt_pk_bf16_f32 v232, v132, v133
	v_cvt_pk_bf16_f32 v233, v134, v135
	s_waitcnt lgkmcnt(0)
	v_mfma_f32_32x32x16_bf16 v[144:159], v[238:241], v[164:167], v[144:159]
	v_mfma_f32_32x32x16_bf16 v[144:159], v[242:245], v[160:163], v[144:159]
	s_waitcnt vmcnt(0)
	s_barrier
; #define SBAR() __builtin_amdgcn_sched_barrier(0)
; #define PVR(S, DA, DB, vbase) do { S[0] = tr_read<v_rd_off(DA, 0, 0)>(vbase); S[1] = tr_read<v_rd_off(DA, 0, 1)>(vbase); S[2] = tr_read<v_rd_off(DB, 0, 0)>(vbase); S[3] = tr_read<v_rd_off(DB, 0, 1)>(vbase); \
;     S[4] = tr_read<v_rd_off(DA, 1, 0)>(vbase); S[5] = tr_read<v_rd_off(DA, 1, 1)>(vbase); S[6] = tr_read<v_rd_off(DB, 1, 0)>(vbase); S[7] = tr_read<v_rd_off(DB, 1, 1)>(vbase); } while (0)
; #define RAWBAR() do { asm volatile("s_waitcnt lgkmcnt(0)" ::: "memory"); __builtin_amdgcn_s_barrier(); asm volatile("" ::: "memory"); } while (0)
; #define RAWBAR() do { asm volatile("s_waitcnt lgkmcnt(0)" ::: "memory"); __builtin_amdgcn_s_barrier(); asm volatile("" ::: "memory"); } while (0)
; #define RAWBAR() do { asm volatile("s_waitcnt lgkmcnt(0)" ::: "memory"); __builtin_amdgcn_s_barrier(); asm volatile("" ::: "memory"); } while (0)
; #define RAWBAR() do { asm volatile("s_waitcnt lgkmcnt(0)" ::: "memory"); __builtin_amdgcn_s_barrier(); asm volatile("" ::: "memory"); } while (0)
; #define RAWBAR() do { asm volatile("s_waitcnt lgkmcnt(0)" ::: "memory"); __builtin_amdgcn_s_barrier(); asm volatile("" ::: "memory"); } while (0)
; template <int MODE> ...
;     ...
;   for (int j = 0; j < NT; ++j) {
;     const int buf = j & 1;
;     if (j + 1 < NT) { STAGE((j + 1) * KVBLK, buf ^ 1); }
;     const char* Kb = K_lds + buf * 16384;
;     f32x16 pe = {}, po = {};
; #pragma unroll
;     for (int d0 = 0; d0 < 8; d0 += 2) {
;       const bf16x8 k0 = *reinterpret_cast<const bf16x8*>(Kb + KSWZ(krow, (d0 * 16 + hi * 8) * 2));
;       const bf16x8 k1 = *reinterpret_cast<const bf16x8*>(Kb + KSWZ(krow, ((d0 + 1) * 16 + hi * 8) * 2));
;       pe = __builtin_amdgcn_mfma_f32_32x32x16_bf16(k0, qr[d0], pe, 0, 0, 0);
;       po = __builtin_amdgcn_mfma_f32_32x32x16_bf16(k1, qr[d0 + 1], po, 0, 0, 0); }
;     const int vo = vb0 + buf * 32768;
;     s16x4 R0_[8], R1_[8];
;     PVR(R0_, 0, 1, vo);
;     f32x16 p;
; #pragma unroll
;     for (int r = 0; r < 16; ++r) p[r] = __builtin_amdgcn_exp2f(fmaf(pe[r] + po[r], C, negMc));
;     float ps = 0.f;
; #pragma unroll
;     for (int r = 0; r < 16; ++r) ps += p[r];
;     lsum += ps;
;     const bf16x8 own0 = pk8(p, 0), own1 = pk8(p, 8);
;     SBAR();
;     PV_TAIL4(o, vo, vo + 16384, own0, own1);
;     asm volatile("s_waitcnt vmcnt(0)" ::: "memory");
;     RAWBAR();
;   }
	s_add_u32 s86, s86, 0x4000
	s_addc_u32 s87, s87, 0
	s_add_u32 s2, s2, 0x8000
	s_addc_u32 s3, s3, 0
	s_mov_b32 m0, s34
	s_nop 0
	global_load_lds_dwordx4 v225, s[86:87]
	s_add_i32 m0, s34, 0x2000
	s_nop 0
	global_load_lds_dwordx4 v223, s[86:87]
	v_add_u32_e32 v249, s84, v218
	s_sub_u32 s85, s84, 0x8000
	s_cmp_eq_u32 s84, 0
	s_cselect_b32 s85, 0x10000, s85
	ds_read_b64_tr_b16 v[238:239], v249 offset:0
	ds_read_b64_tr_b16 v[240:241], v249 offset:2048
	ds_read_b64_tr_b16 v[242:243], v249 offset:512
	ds_read_b64_tr_b16 v[244:245], v249 offset:2560
	v_permlane32_swap_b32_e32 v230, v232
	v_permlane32_swap_b32_e32 v231, v233
	ds_read_b64_tr_b16 v[128:129], v249 offset:4096
	ds_read_b64_tr_b16 v[130:131], v249 offset:6144
	ds_read_b64_tr_b16 v[132:133], v249 offset:4608
	ds_read_b64_tr_b16 v[134:135], v249 offset:6656
	v_add_f32_e32 v250, v140, v250
	v_add_f32_e32 v250, v141, v250
	v_add_f32_e32 v250, v142, v250
	v_add_f32_e32 v250, v143, v250
	v_cvt_pk_bf16_f32 v234, v136, v137
	v_cvt_pk_bf16_f32 v235, v138, v139
	v_cvt_pk_bf16_f32 v236, v140, v141
	v_cvt_pk_bf16_f32 v237, v142, v143
	v_add_f32_e32 v219, v219, v250
	ds_read_b64_tr_b16 v[136:137], v249 offset:1024
	ds_read_b64_tr_b16 v[138:139], v249 offset:3072
	ds_read_b64_tr_b16 v[140:141], v249 offset:1536
	ds_read_b64_tr_b16 v[142:143], v249 offset:3584
	v_permlane32_swap_b32_e32 v234, v236
	v_permlane32_swap_b32_e32 v235, v237
	s_waitcnt lgkmcnt(8)
	v_mfma_f32_32x32x16_bf16 v[112:127], v[230:233], v[238:241], v[112:127]
	v_mfma_f32_32x32x16_bf16 v[96:111], v[230:233], v[242:245], v[96:111]
	ds_read_b64_tr_b16 v[238:239], v249 offset:5120
	ds_read_b64_tr_b16 v[240:241], v249 offset:7168
	ds_read_b64_tr_b16 v[242:243], v249 offset:5632
	ds_read_b64_tr_b16 v[244:245], v249 offset:7680
	s_add_i32 s30, s85, s34
	s_add_i32 m0, s30, 0x8000
	s_nop 0
	global_load_lds_dwordx4 v222, s[2:3]
	s_waitcnt lgkmcnt(8)
	v_mfma_f32_32x32x16_bf16 v[112:127], v[234:237], v[128:131], v[112:127]
	v_mfma_f32_32x32x16_bf16 v[96:111], v[234:237], v[132:135], v[96:111]
	ds_read_b64_tr_b16 v[128:129], v249 offset:16384
	ds_read_b64_tr_b16 v[130:131], v249 offset:18432
	ds_read_b64_tr_b16 v[132:133], v249 offset:16896
	ds_read_b64_tr_b16 v[134:135], v249 offset:18944
	s_add_i32 s30, s85, s34
	s_add_i32 m0, s30, 0xa000
	s_nop 0
	global_load_lds_dwordx4 v221, s[2:3]
	s_waitcnt lgkmcnt(8)
	v_mfma_f32_32x32x16_bf16 v[80:95], v[230:233], v[136:139], v[80:95]
	v_mfma_f32_32x32x16_bf16 v[64:79], v[230:233], v[140:143], v[64:79]
	ds_read_b64_tr_b16 v[136:137], v249 offset:20480
	ds_read_b64_tr_b16 v[138:139], v249 offset:22528
	ds_read_b64_tr_b16 v[140:141], v249 offset:20992
	ds_read_b64_tr_b16 v[142:143], v249 offset:23040
	s_add_i32 s30, s85, s34
	s_add_i32 m0, s30, 0xc000
	s_nop 0
	global_load_lds_dwordx4 v246, s[2:3]
	s_waitcnt lgkmcnt(8)
	v_mfma_f32_32x32x16_bf16 v[80:95], v[234:237], v[238:241], v[80:95]
	v_mfma_f32_32x32x16_bf16 v[64:79], v[234:237], v[242:245], v[64:79]
	ds_read_b64_tr_b16 v[238:239], v249 offset:17408
	ds_read_b64_tr_b16 v[240:241], v249 offset:19456
	ds_read_b64_tr_b16 v[242:243], v249 offset:17920
	ds_read_b64_tr_b16 v[244:245], v249 offset:19968
	s_add_i32 s30, s85, s34
	s_add_i32 m0, s30, 0xe000
	s_nop 0
	global_load_lds_dwordx4 v247, s[2:3]
	s_waitcnt lgkmcnt(8)
	v_mfma_f32_32x32x16_bf16 v[32:47], v[230:233], v[128:131], v[32:47]
	v_mfma_f32_32x32x16_bf16 v[16:31], v[230:233], v[132:135], v[16:31]
	ds_read_b64_tr_b16 v[128:129], v249 offset:21504
	ds_read_b64_tr_b16 v[130:131], v249 offset:23552
	ds_read_b64_tr_b16 v[132:133], v249 offset:22016
	ds_read_b64_tr_b16 v[134:135], v249 offset:24064
	s_waitcnt lgkmcnt(8)
	v_mfma_f32_32x32x16_bf16 v[32:47], v[234:237], v[136:139], v[32:47]
	v_mfma_f32_32x32x16_bf16 v[16:31], v[234:237], v[140:143], v[16:31]
	s_waitcnt lgkmcnt(0)
	v_mfma_f32_32x32x16_bf16 v[48:63], v[230:233], v[238:241], v[48:63]
	v_mfma_f32_32x32x16_bf16 v[0:15], v[230:233], v[242:245], v[0:15]
	v_mfma_f32_32x32x16_bf16 v[48:63], v[234:237], v[128:131], v[48:63]
	v_mfma_f32_32x32x16_bf16 v[0:15], v[234:237], v[132:135], v[0:15]
	s_add_i32 s84, s84, 0x8000
	s_cmp_eq_u32 s84, 0x18000
	s_cselect_b32 s84, 0, s84
	s_add_i32 s40, s40, 1
	s_cmpk_eq_i32 s40, 0x82
	s_cbranch_scc0 .LattnB_m1
	s_waitcnt vmcnt(0)
	s_barrier
